# attention main loop: -mhat enters via the QK MFMA C operand, 32 v_sub per tile-step removed (3 copies)
# speedup vs baseline: 1.0195x; 1.0195x over previous
; __device__ __forceinline__ float max3f(float a,float b,float c){float r;asm("v_max3_f32 %0, %1, %2, %3":"=v"(r):"v"(a),"v"(b),"v"(c));return r;}
; #define SB() __builtin_amdgcn_sched_barrier(0)
; #define EXP1(x) x=__builtin_amdgcn_exp2f((x)-mh_)
; template<int THRL,bool FIRST> __device__ __forceinline__ void step_main(f32x16&p0,f32x16&p1,f32x16&n0,f32x16&n1,St&S,lds_cptr kpn,lds_cptr qp,lds_cptr vp,float*wsf,int r32,int hi,float&rm){
;     ...
;   bf16x8 ka=KF(0),kb=KF(1),kc=KF(2),kd=KF(3),qa=QF(0),qb=QF(1);
;   decide<THRL,FIRST>(rm,S,wsf,r32,hi);
;   u32x4 pw0,pw1,pw2,pw3; const float mh_=S.mhat; const f32x16 z=f32x16{};
;   SB();
;   n0=MF32(ka,qa,z); ka=KF(4); EXP1(p0[0]);EXP1(p0[1]);EXP1(p0[2]); SB();
;   n1=MF32(kb,qa,z); kb=KF(5); qa=QF(2); EXP1(p0[3]);EXP1(p0[4]);EXP1(p0[5]); SB();
;   n0=MF32(kc,qb,n0);   kc=KF(6); EXP1(p0[6]);EXP1(p0[7]);EXP1(p0[8]); SB();
;   n1=MF32(kd,qb,n1);   kd=KF(7); qb=QF(3); EXP1(p0[9]);EXP1(p0[10]);EXP1(p0[11]); SB();
;   bf16x8 vfa=vfrag(vp,0);
;   n0=MF32(ka,qa,n0);   EXP1(p0[12]);EXP1(p0[13]);EXP1(p0[14]); pw0=packw(p0,0); SB();
;   bf16x8 vfb=vfrag(vp,1);
;   n1=MF32(kb,qa,n1);   EXP1(p0[15]);EXP1(p1[0]);EXP1(p1[1]); SB();
;   bf16x8 vfc=vfrag(vp,2);
;   n0=MF32(kc,qb,n0);   EXP1(p1[2]);EXP1(p1[3]);EXP1(p1[4]); pw1=packw(p0,8); SB();
;   bf16x8 vfd=vfrag(vp,3);
;   n1=MF32(kd,qb,n1);   EXP1(p1[5]);EXP1(p1[6]);EXP1(p1[7]); SB();
;     ...
;   float sa=p0[0]+p0[1];
;     ...
;   PVG(0,pw0,vfa,4, p0[2],p0[3],p0[4],p0[5],   do{EXP1(p1[8]);EXP1(p1[9]);}while(0));
;   PVG(1,pw0,vfb,5, p0[6],p0[7],p0[8],p0[9], do{EXP1(p1[10]);EXP1(p1[11]);}while(0));
;   PVG(2,pw0,vfc,6, p0[10],p0[11],p0[12],p0[13], do{EXP1(p1[12]);EXP1(p1[13]);}while(0));
;   PVG(3,pw0,vfd,7, p0[14],p0[15],p1[0],p1[1],   do{EXP1(p1[14]);EXP1(p1[15]);}while(0));
;   PVG(4,pw1,vfa,8, p1[2],p1[3],p1[4],p1[5],   pw2=packw(p1,0));
;   PVG(5,pw1,vfb,9, p1[6],p1[7],p1[8],p1[9], pw3=packw(p1,8));
;   PVG(6,pw1,vfc,10, p1[10],p1[11],p1[12],p1[13], do{}while(0));
;   PVG(7,pw1,vfd,11, p1[14],p1[15],0.f,0.f, do{}while(0));
;   float ma,mb;
;     ...
;   PVG(8,pw2,vfa,12,0.f,0.f,0.f,0.f, do{ma=max3f(n0[0],n0[1],n1[0]);mb=max3f(n0[2],n0[3],n1[1]);PINAB();}while(0));
;   PVG(9,pw2,vfb,13,0.f,0.f,0.f,0.f, do{ma=max3f(ma,n1[2],n1[3]);mb=max3f(mb,n0[4],n0[5]);PINAB();}while(0));
;   PVG(10,pw2,vfc,14,0.f,0.f,0.f,0.f, do{ma=max3f(ma,n0[6],n0[7]);mb=max3f(mb,n1[4],n1[5]);PINAB();}while(0));
.LBB0_275:
	s_waitcnt lgkmcnt(1)
	v_mfma_f32_32x32x16_bf16 v[98:113], v[218:221], v[214:217], 0
	ds_read_b128 v[178:181], v249 offset:20480
	v_sub_f32_e32 v82, v131, v247
	v_sub_f32_e32 v17, v130, v247
	v_exp_f32_e32 v190, v82
	v_sub_f32_e32 v82, v132, v247
	v_exp_f32_e32 v17, v17
	v_exp_f32_e32 v191, v82
	v_sub_f32_e32 v82, v133, v247
	v_exp_f32_e32 v192, v82
	v_sub_f32_e32 v82, v134, v247
	v_exp_f32_e32 v193, v82
	v_sub_f32_e32 v82, v135, v247
	v_exp_f32_e32 v194, v82
	v_mfma_f32_32x32x16_bf16 v[82:97], v[210:213], v[214:217], 0
	ds_read_b128 v[182:185], v249 offset:20992
	ds_read_b128 v[186:189], v248 offset:2048
	s_waitcnt lgkmcnt(3)
	v_mfma_f32_32x32x16_bf16 v[98:113], v[12:15], v[8:11], v[98:113]
	ds_read_b128 v[130:133], v249 offset:22528
	v_sub_f32_e32 v134, v136, v247
	v_exp_f32_e32 v195, v134
	v_sub_f32_e32 v134, v137, v247
	v_exp_f32_e32 v196, v134
	v_sub_f32_e32 v134, v138, v247
	v_exp_f32_e32 v197, v134
	v_mfma_f32_32x32x16_bf16 v[82:97], v[4:7], v[8:11], v[82:97]
	ds_read_b128 v[12:15], v249 offset:23040
	ds_read_b128 v[134:137], v248 offset:3072
	v_sub_f32_e32 v138, v139, v247
	v_exp_f32_e32 v198, v138
	v_sub_f32_e32 v138, v140, v247
	v_exp_f32_e32 v199, v138
	v_sub_f32_e32 v138, v141, v247
	v_exp_f32_e32 v200, v138
	s_waitcnt lgkmcnt(3)
	v_mfma_f32_32x32x16_bf16 v[98:113], v[178:181], v[186:189], v[98:113]
	ds_read_b64_tr_b16 v[4:5], v246 offset:40960
	ds_read_b64_tr_b16 v[6:7], v246 offset:41472
	v_sub_f32_e32 v8, v142, v247
	v_exp_f32_e32 v201, v8
	v_sub_f32_e32 v8, v143, v247
	v_exp_f32_e32 v202, v8
	v_sub_f32_e32 v8, v144, v247
	v_exp_f32_e32 v179, v8
	v_cvt_pk_bf16_f32 v8, v17, v190
	v_cvt_pk_bf16_f32 v9, v191, v192
	v_cvt_pk_bf16_f32 v10, v193, v194
	v_cvt_pk_bf16_f32 v11, v195, v196
	v_mfma_f32_32x32x16_bf16 v[82:97], v[182:185], v[186:189], v[82:97]
	ds_read_b64_tr_b16 v[138:139], v246 offset:45056
	ds_read_b64_tr_b16 v[140:141], v246 offset:45568
	v_sub_f32_e32 v114, v114, v247
	v_sub_f32_e32 v142, v145, v247
	v_exp_f32_e32 v181, v114
	v_sub_f32_e32 v114, v115, v247
	v_exp_f32_e32 v180, v142
	v_exp_f32_e32 v203, v114
	s_waitcnt lgkmcnt(4)
	v_mfma_f32_32x32x16_bf16 v[98:113], v[130:133], v[134:137], v[98:113]
	ds_read_b64_tr_b16 v[142:143], v246 offset:49152
	ds_read_b64_tr_b16 v[144:145], v246 offset:49664
	v_sub_f32_e32 v114, v116, v247
	v_exp_f32_e32 v182, v114
	v_sub_f32_e32 v114, v117, v247
	v_exp_f32_e32 v183, v114
	v_sub_f32_e32 v114, v118, v247
	v_exp_f32_e32 v184, v114
	v_cvt_pk_bf16_f32 v114, v197, v198
	v_cvt_pk_bf16_f32 v115, v199, v200
	v_cvt_pk_bf16_f32 v116, v201, v202
	v_cvt_pk_bf16_f32 v117, v179, v180
	v_mfma_f32_32x32x16_bf16 v[82:97], v[12:15], v[134:137], v[82:97]
	ds_read_b64_tr_b16 v[130:131], v246 offset:53248
	ds_read_b64_tr_b16 v[132:133], v246 offset:53760
	v_sub_f32_e32 v118, v119, v247
	v_exp_f32_e32 v185, v118
	v_sub_f32_e32 v118, v120, v247
	v_exp_f32_e32 v186, v118
	v_sub_f32_e32 v118, v121, v247
	v_exp_f32_e32 v187, v118
	s_waitcnt lgkmcnt(6)
	v_mfma_f32_32x32x16_bf16 v[18:33], v[8:11], v[4:7], v[18:33]
	ds_read_b64_tr_b16 v[12:13], v246 offset:41984
	ds_read_b64_tr_b16 v[14:15], v246 offset:42496
	v_sub_f32_e32 v118, v122, v247
	v_exp_f32_e32 v134, v118
	v_sub_f32_e32 v118, v123, v247
	v_exp_f32_e32 v135, v118
	s_waitcnt lgkmcnt(6)
	v_mfma_f32_32x32x16_bf16 v[34:49], v[8:11], v[138:141], v[34:49]
	ds_read_b64_tr_b16 v[4:5], v246 offset:46080
	ds_read_b64_tr_b16 v[6:7], v246 offset:46592
	v_sub_f32_e32 v118, v124, v247
	v_exp_f32_e32 v136, v118
	v_sub_f32_e32 v118, v125, v247
	v_exp_f32_e32 v137, v118
	s_waitcnt lgkmcnt(6)
	v_mfma_f32_32x32x16_bf16 v[50:65], v[8:11], v[142:145], v[50:65]
	ds_read_b64_tr_b16 v[118:119], v246 offset:50176
	ds_read_b64_tr_b16 v[120:121], v246 offset:50688
	v_sub_f32_e32 v122, v126, v247
	v_exp_f32_e32 v138, v122
	v_sub_f32_e32 v122, v127, v247
	v_exp_f32_e32 v139, v122
	s_waitcnt lgkmcnt(6)
	v_mfma_f32_32x32x16_bf16 v[66:81], v[8:11], v[130:133], v[66:81]
	ds_read_b64_tr_b16 v[122:123], v246 offset:54272
	ds_read_b64_tr_b16 v[124:125], v246 offset:54784
	v_sub_f32_e32 v126, v128, v247
	v_exp_f32_e32 v140, v126
	v_sub_f32_e32 v126, v129, v247
	v_exp_f32_e32 v141, v126
	s_waitcnt lgkmcnt(6)
	v_mfma_f32_32x32x16_bf16 v[18:33], v[114:117], v[12:15], v[18:33]
	ds_read_b64_tr_b16 v[8:9], v246 offset:43008
	ds_read_b64_tr_b16 v[10:11], v246 offset:43520
	v_cvt_pk_bf16_f32 v126, v181, v203
	v_cvt_pk_bf16_f32 v127, v182, v183
	v_cvt_pk_bf16_f32 v128, v184, v185
	v_cvt_pk_bf16_f32 v129, v186, v187
	s_waitcnt lgkmcnt(6)
	v_mfma_f32_32x32x16_bf16 v[34:49], v[114:117], v[4:7], v[34:49]
	ds_read_b64_tr_b16 v[12:13], v246 offset:47104
	ds_read_b64_tr_b16 v[14:15], v246 offset:47616
	v_cvt_pk_bf16_f32 v130, v134, v135
	v_cvt_pk_bf16_f32 v131, v136, v137
	v_cvt_pk_bf16_f32 v132, v138, v139
	v_cvt_pk_bf16_f32 v133, v140, v141
	s_waitcnt lgkmcnt(6)
	v_mfma_f32_32x32x16_bf16 v[50:65], v[114:117], v[118:121], v[50:65]
	ds_read_b64_tr_b16 v[4:5], v246 offset:51200
	ds_read_b64_tr_b16 v[6:7], v246 offset:51712
	s_waitcnt lgkmcnt(6)
	v_mfma_f32_32x32x16_bf16 v[66:81], v[114:117], v[122:125], v[66:81]
	ds_read_b64_tr_b16 v[118:119], v246 offset:55296
	ds_read_b64_tr_b16 v[120:121], v246 offset:55808
	s_waitcnt lgkmcnt(6)
	v_mfma_f32_32x32x16_bf16 v[18:33], v[126:129], v[8:11], v[18:33]
	ds_read_b64_tr_b16 v[114:115], v246 offset:44032
	ds_read_b64_tr_b16 v[116:117], v246 offset:44544
	v_max3_f32 v122, v98, v99, v82
	v_max3_f32 v123, v100, v101, v83
	s_nop 0
	s_waitcnt lgkmcnt(6)
	v_mfma_f32_32x32x16_bf16 v[34:49], v[126:129], v[12:15], v[34:49]
	ds_read_b64_tr_b16 v[8:9], v246 offset:48128
	ds_read_b64_tr_b16 v[10:11], v246 offset:48640
	v_max3_f32 v122, v122, v84, v85
	v_max3_f32 v123, v123, v102, v103
	s_nop 0
	s_waitcnt lgkmcnt(6)
; __device__ __forceinline__ int crow(int r,int hi){return (r&3)+8*(r>>2)+4*hi;}
; __device__ __forceinline__ float max3f(float a,float b,float c){float r;asm("v_max3_f32 %0, %1, %2, %3":"=v"(r):"v"(a),"v"(b),"v"(c));return r;}
; __device__ __forceinline__ float max2f(float a,float b){float r;asm("v_max_f32_e32 %0, %1, %2":"=v"(r):"v"(a),"v"(b));return r;}
;   #define PVG(i,PW,VF,NEXTI,X0,X1,Y0,Y1,EXTRA) do{ S.o[(i)&3]=MF32(__builtin_bit_cast(bf16x8,PW),VF,S.o[(i)&3]); if((NEXTI)<16){ VF=vfrag(vp,(NEXTI)<16?(NEXTI):0); } sa+=X0; sa+=X1; sa+=Y0; sa+=Y1; EXTRA; SB(); }while(0)
; template<int THRL,bool FIRST> __device__ __forceinline__ void decide(float rm,St&S,float*wsf,int r32,int hi){
;     ...
;   else if(__any(rm-S.mhat>(float)THRL)){
;     const float dl=__builtin_fmaxf(rm-S.mhat,0.f); S.mhat+=dl;
;     const float f=__builtin_amdgcn_exp2f(-dl); S.l_reg*=f; if(hi==0)wsf[r32]=f;
;     asm volatile("s_waitcnt lgkmcnt(0)":::"memory");
;     #pragma unroll
;     for(int r=0;r<16;++r){ const float fr=wsf[crow(r,hi)];
;       #pragma unroll
;       for(int d=0;d<4;++d)S.o[d][r]*=fr; }
; template<int THRL,bool FIRST> __device__ __forceinline__ void step_main(f32x16&p0,f32x16&p1,f32x16&n0,f32x16&n1,St&S,lds_cptr kpn,lds_cptr qp,lds_cptr vp,float*wsf,int r32,int hi,float&rm){
;     ...
;   PVG(8,pw2,vfa,12,0.f,0.f,0.f,0.f, do{ma=max3f(n0[0],n0[1],n1[0]);mb=max3f(n0[2],n0[3],n1[1]);PINAB();}while(0));
;   PVG(9,pw2,vfb,13,0.f,0.f,0.f,0.f, do{ma=max3f(ma,n1[2],n1[3]);mb=max3f(mb,n0[4],n0[5]);PINAB();}while(0));
;   PVG(10,pw2,vfc,14,0.f,0.f,0.f,0.f, do{ma=max3f(ma,n0[6],n0[7]);mb=max3f(mb,n1[4],n1[5]);PINAB();}while(0));
;   PVG(11,pw2,vfd,15,0.f,0.f,0.f,0.f, do{ma=max3f(ma,n1[6],n1[7]);mb=max3f(mb,n0[8],n0[9]);PINAB();}while(0));
;   PVG(12,pw3,vfa,16,0.f,0.f,0.f,0.f, do{ma=max3f(ma,n0[10],n0[11]);mb=max3f(mb,n1[8],n1[9]);PINAB();}while(0));
;   PVG(13,pw3,vfb,16,0.f,0.f,0.f,0.f, do{ma=max3f(ma,n1[10],n1[11]);mb=max3f(mb,n0[12],n0[13]);PINAB();}while(0));
;   PVG(14,pw3,vfc,16,0.f,0.f,0.f,0.f, do{ma=max3f(ma,n0[14],n0[15]);mb=max3f(mb,n1[12],n1[13]);PINAB();}while(0));
;   PVG(15,pw3,vfd,16,0.f,0.f,0.f,0.f, do{ma=max3f(ma,n1[14],n1[15]);ma=max2f(ma,mb);PINAB();}while(0));
;     ...
;   { auto rr=__builtin_amdgcn_permlane32_swap(__float_as_uint(ma),__float_as_uint(ma),false,false); rm=max2f(__uint_as_float(rr[0]),__uint_as_float(rr[1])); }
;     ...
;   S.l_reg+=sa;
	v_mfma_f32_32x32x16_bf16 v[50:65], v[126:129], v[4:7], v[50:65]
	ds_read_b64_tr_b16 v[12:13], v246 offset:52224
	ds_read_b64_tr_b16 v[14:15], v246 offset:52736
	v_max3_f32 v122, v122, v104, v105
	v_max3_f32 v123, v123, v86, v87
	s_nop 0
	s_waitcnt lgkmcnt(6)
	v_mfma_f32_32x32x16_bf16 v[66:81], v[126:129], v[118:121], v[66:81]
	ds_read_b64_tr_b16 v[4:5], v246 offset:56320
	ds_read_b64_tr_b16 v[6:7], v246 offset:56832
	v_max3_f32 v122, v122, v88, v89
	v_max3_f32 v123, v123, v106, v107
	s_nop 0
	s_waitcnt lgkmcnt(6)
	v_mfma_f32_32x32x16_bf16 v[18:33], v[130:133], v[114:117], v[18:33]
	v_max3_f32 v118, v122, v108, v109
	v_max3_f32 v119, v123, v90, v91
	s_nop 0
	s_waitcnt lgkmcnt(4)
	v_mfma_f32_32x32x16_bf16 v[34:49], v[130:133], v[8:11], v[34:49]
	v_max3_f32 v114, v118, v92, v93
	v_max3_f32 v115, v119, v110, v111
	s_nop 0
	s_waitcnt lgkmcnt(2)
	v_mfma_f32_32x32x16_bf16 v[50:65], v[130:133], v[12:15], v[50:65]
	v_max3_f32 v8, v114, v112, v113
	v_max3_f32 v9, v115, v94, v95
	s_nop 0
	s_waitcnt lgkmcnt(0)
	v_mfma_f32_32x32x16_bf16 v[66:81], v[130:133], v[4:7], v[66:81]
	v_max3_f32 v8, v8, v96, v97
	s_nop 0
	v_max_f32_e32 v8, v8, v9
	s_nop 0
	s_nop 0
	v_mov_b32_e32 v4, v8
	s_nop 1
	v_permlane32_swap_b32_e32 v8, v4
	v_max_f32_e32 v178, v8, v4
	v_add_f32_e32 v4, v17, v190
	v_add_f32_e32 v4, v191, v4
	v_add_f32_e32 v4, v192, v4
	v_add_f32_e32 v4, v193, v4
	v_add_f32_e32 v4, v194, v4
	v_add_f32_e32 v4, v195, v4
	v_add_f32_e32 v4, v196, v4
	v_add_f32_e32 v4, v197, v4
	v_add_f32_e32 v4, v198, v4
	v_add_f32_e32 v4, v199, v4
	v_add_f32_e32 v4, v200, v4
	v_add_f32_e32 v4, v201, v4
	v_add_f32_e32 v4, v202, v4
	v_add_f32_e32 v4, v179, v4
	v_add_f32_e32 v4, v180, v4
	v_add_f32_e32 v4, v181, v4
	v_add_f32_e32 v4, v203, v4
	v_add_f32_e32 v4, v182, v4
	v_add_f32_e32 v4, v183, v4
	v_add_f32_e32 v4, v184, v4
	v_add_f32_e32 v4, v185, v4
	v_add_f32_e32 v4, v186, v4
	v_add_f32_e32 v4, v187, v4
	v_add_f32_e32 v4, v134, v4
	v_add_f32_e32 v4, v135, v4
	v_add_f32_e32 v4, v136, v4
	v_add_f32_e32 v4, v137, v4
	v_add_f32_e32 v4, v138, v4
	v_add_f32_e32 v4, v139, v4
	v_add_f32_e32 v4, v140, v4
	s_waitcnt vmcnt(0) lgkmcnt(0)
	s_barrier
	v_add_f32_e32 v4, v141, v4
	v_add_f32_e32 v4, 0, v4
	s_add_i32 s89, s85, -4
	v_add_f32_e32 v251, v16, v4
	v_cmp_gt_u32_e64 s[6:7], 32, v243
	s_mov_b32 s90, 2
	v_lshl_add_u32 v16, v242, 2, s78
	s_movk_i32 s88, 0x2000
	s_mov_b32 s91, 0
	s_mov_b64 s[50:51], s[30:31]
	s_mov_b64 s[58:59], s[28:29]
	v_sub_f32_e32 v146, 0, v247
	v_sub_f32_e32 v147, 0, v247
	v_sub_f32_e32 v148, 0, v247
	v_sub_f32_e32 v149, 0, v247
	v_sub_f32_e32 v150, 0, v247
	v_sub_f32_e32 v151, 0, v247
	v_sub_f32_e32 v152, 0, v247
	v_sub_f32_e32 v153, 0, v247
	v_sub_f32_e32 v154, 0, v247
	v_sub_f32_e32 v155, 0, v247
	v_sub_f32_e32 v156, 0, v247
	v_sub_f32_e32 v157, 0, v247
	v_sub_f32_e32 v158, 0, v247
	v_sub_f32_e32 v159, 0, v247
	v_sub_f32_e32 v160, 0, v247
	v_sub_f32_e32 v161, 0, v247
	v_sub_f32_e32 v82, v82, v247
	v_sub_f32_e32 v83, v83, v247
	v_sub_f32_e32 v84, v84, v247
	v_sub_f32_e32 v85, v85, v247
	v_sub_f32_e32 v86, v86, v247
	v_sub_f32_e32 v87, v87, v247
	v_sub_f32_e32 v88, v88, v247
	v_sub_f32_e32 v89, v89, v247
	v_sub_f32_e32 v90, v90, v247
	v_sub_f32_e32 v91, v91, v247
	v_sub_f32_e32 v92, v92, v247
	v_sub_f32_e32 v93, v93, v247
	v_sub_f32_e32 v94, v94, v247
	v_sub_f32_e32 v95, v95, v247
	v_sub_f32_e32 v96, v96, v247
	v_sub_f32_e32 v97, v97, v247
	v_sub_f32_e32 v98, v98, v247
	v_sub_f32_e32 v99, v99, v247
	v_sub_f32_e32 v100, v100, v247
	v_sub_f32_e32 v101, v101, v247
	v_sub_f32_e32 v102, v102, v247
	v_sub_f32_e32 v103, v103, v247
	v_sub_f32_e32 v104, v104, v247
	v_sub_f32_e32 v105, v105, v247
	v_sub_f32_e32 v106, v106, v247
	v_sub_f32_e32 v107, v107, v247
	v_sub_f32_e32 v108, v108, v247
	v_sub_f32_e32 v109, v109, v247
	v_sub_f32_e32 v110, v110, v247
	v_sub_f32_e32 v111, v111, v247
	v_sub_f32_e32 v112, v112, v247
	v_sub_f32_e32 v113, v113, v247
	v_sub_f32_e32 v178, v178, v247
	s_branch .LBB0_278
.LBB0_276:
	s_or_b64 exec, exec, s[60:61]
	s_waitcnt lgkmcnt(0)
	v_add_u32_e32 v108, s78, v2
	ds_read_b128 v[96:99], v108 offset:64
	ds_read_b128 v[100:103], v108 offset:96
	ds_read_b128 v[104:107], v108
	ds_read_b128 v[108:111], v108 offset:32
	v_add_f32_e32 v247, v247, v94
	v_sub_f32_e32 v146, v146, v94
	v_sub_f32_e32 v147, v147, v94
	v_sub_f32_e32 v148, v148, v94
	v_sub_f32_e32 v149, v149, v94
	v_sub_f32_e32 v150, v150, v94
	v_sub_f32_e32 v151, v151, v94
	v_sub_f32_e32 v152, v152, v94
	v_sub_f32_e32 v153, v153, v94
	v_sub_f32_e32 v154, v154, v94
	v_sub_f32_e32 v155, v155, v94
	v_sub_f32_e32 v156, v156, v94
	v_sub_f32_e32 v157, v157, v94
	v_sub_f32_e32 v158, v158, v94
	v_sub_f32_e32 v159, v159, v94
	v_sub_f32_e32 v160, v160, v94
	v_sub_f32_e32 v161, v161, v94
	v_sub_f32_e32 v114, v114, v94
	v_sub_f32_e32 v115, v115, v94
	v_sub_f32_e32 v116, v116, v94
	v_sub_f32_e32 v117, v117, v94
	v_sub_f32_e32 v118, v118, v94
	v_sub_f32_e32 v119, v119, v94
	v_sub_f32_e32 v120, v120, v94
	v_sub_f32_e32 v121, v121, v94
	v_sub_f32_e32 v122, v122, v94
	v_sub_f32_e32 v123, v123, v94
	v_sub_f32_e32 v124, v124, v94
	v_sub_f32_e32 v125, v125, v94
	v_sub_f32_e32 v126, v126, v94
	v_sub_f32_e32 v127, v127, v94
	v_sub_f32_e32 v128, v128, v94
	v_sub_f32_e32 v129, v129, v94
	v_sub_f32_e32 v130, v130, v94
	v_sub_f32_e32 v131, v131, v94
	v_sub_f32_e32 v132, v132, v94
	v_sub_f32_e32 v133, v133, v94
	v_sub_f32_e32 v134, v134, v94
	v_sub_f32_e32 v135, v135, v94
	v_sub_f32_e32 v136, v136, v94
	v_sub_f32_e32 v137, v137, v94
	v_sub_f32_e32 v138, v138, v94
	v_sub_f32_e32 v139, v139, v94
	v_sub_f32_e32 v140, v140, v94
	v_sub_f32_e32 v141, v141, v94
	v_sub_f32_e32 v142, v142, v94
	v_sub_f32_e32 v143, v143, v94
	v_sub_f32_e32 v144, v144, v94
	v_sub_f32_e32 v145, v145, v94
	v_mul_f32_e32 v17, v17, v95
	s_waitcnt lgkmcnt(2)
; #define SB() __builtin_amdgcn_sched_barrier(0)
; #define MF32(a,b,c) __builtin_amdgcn_mfma_f32_32x32x16_bf16(a,b,c,0,0,0)
; #define EXP1(x) x=__builtin_amdgcn_exp2f((x)-mh_)
; __device__ __forceinline__ bf16x8 vfrag(lds_cptr vp,int i){ const s16x4 lo=vtr(vp+(i&3)*4096+(i>>2)*1024), hh=vtr(vp+(i&3)*4096+(i>>2)*1024+512); return (bf16x8){lo[0],lo[1],lo[2],lo[3],hh[0],hh[1],hh[2],hh[3]}; }
; __device__ __forceinline__ u32x4 packw(const f32x16&p,int base){ u32x4 w; w[0]=cvtpk_s(p[base],p[base+1]); w[1]=cvtpk_s(p[base+2],p[base+3]); w[2]=cvtpk_s(p[base+4],p[base+5]); w[3]=cvtpk_s(p[base+6],p[base+7]); return w; }
; template<int THRL,bool FIRST> __device__ __forceinline__ void step_main(f32x16&p0,f32x16&p1,f32x16&n0,f32x16&n1,St&S,lds_cptr kpn,lds_cptr qp,lds_cptr vp,float*wsf,int r32,int hi,float&rm){
;     ...
;   bf16x8 ka=KF(0),kb=KF(1),kc=KF(2),kd=KF(3),qa=QF(0),qb=QF(1);
;   decide<THRL,FIRST>(rm,S,wsf,r32,hi);
;   u32x4 pw0,pw1,pw2,pw3; const float mh_=S.mhat; const f32x16 z=f32x16{};
;   SB();
;   n0=MF32(ka,qa,z); ka=KF(4); EXP1(p0[0]);EXP1(p0[1]);EXP1(p0[2]); SB();
;   n1=MF32(kb,qa,z); kb=KF(5); qa=QF(2); EXP1(p0[3]);EXP1(p0[4]);EXP1(p0[5]); SB();
;   n0=MF32(kc,qb,n0);   kc=KF(6); EXP1(p0[6]);EXP1(p0[7]);EXP1(p0[8]); SB();
;   n1=MF32(kd,qb,n1);   kd=KF(7); qb=QF(3); EXP1(p0[9]);EXP1(p0[10]);EXP1(p0[11]); SB();
;   bf16x8 vfa=vfrag(vp,0);
;   n0=MF32(ka,qa,n0);   EXP1(p0[12]);EXP1(p0[13]);EXP1(p0[14]); pw0=packw(p0,0); SB();
;   bf16x8 vfb=vfrag(vp,1);
;   n1=MF32(kb,qa,n1);   EXP1(p0[15]);EXP1(p1[0]);EXP1(p1[1]); SB();
;   bf16x8 vfc=vfrag(vp,2);
;   n0=MF32(kc,qb,n0);   EXP1(p1[2]);EXP1(p1[3]);EXP1(p1[4]); pw1=packw(p0,8); SB();
;   bf16x8 vfd=vfrag(vp,3);
;   n1=MF32(kd,qb,n1);   EXP1(p1[5]);EXP1(p1[6]);EXP1(p1[7]); SB();
;     ...
;   float sa=p0[0]+p0[1];
;     ...
;   PVG(0,pw0,vfa,4, p0[2],p0[3],p0[4],p0[5],   do{EXP1(p1[8]);EXP1(p1[9]);}while(0));
;   PVG(1,pw0,vfb,5, p0[6],p0[7],p0[8],p0[9], do{EXP1(p1[10]);EXP1(p1[11]);}while(0));
;   PVG(2,pw0,vfc,6, p0[10],p0[11],p0[12],p0[13], do{EXP1(p1[12]);EXP1(p1[13]);}while(0));
;   PVG(3,pw0,vfd,7, p0[14],p0[15],p1[0],p1[1],   do{EXP1(p1[14]);EXP1(p1[15]);}while(0));
;   PVG(4,pw1,vfa,8, p1[2],p1[3],p1[4],p1[5],   pw2=packw(p1,0));
;   PVG(5,pw1,vfb,9, p1[6],p1[7],p1[8],p1[9], pw3=packw(p1,8));
;   PVG(6,pw1,vfc,10, p1[10],p1[11],p1[12],p1[13], do{}while(0));
;   PVG(7,pw1,vfd,11, p1[14],p1[15],0.f,0.f, do{}while(0));
	v_pk_mul_f32 v[30:31], v[30:31], v[100:101]
	v_pk_mul_f32 v[26:27], v[26:27], v[96:97]
	s_waitcnt lgkmcnt(0)
	v_pk_mul_f32 v[22:23], v[22:23], v[108:109]
	v_pk_mul_f32 v[32:33], v[32:33], v[102:103]
	v_pk_mul_f32 v[28:29], v[28:29], v[98:99]
	v_pk_mul_f32 v[24:25], v[24:25], v[110:111]
	v_pk_mul_f32 v[20:21], v[20:21], v[106:107]
	v_pk_mul_f32 v[18:19], v[18:19], v[104:105]
	v_pk_mul_f32 v[46:47], v[46:47], v[100:101]
	v_pk_mul_f32 v[42:43], v[42:43], v[96:97]
	v_pk_mul_f32 v[38:39], v[38:39], v[108:109]
	v_pk_mul_f32 v[48:49], v[48:49], v[102:103]
	v_pk_mul_f32 v[44:45], v[44:45], v[98:99]
	v_pk_mul_f32 v[40:41], v[40:41], v[110:111]
	v_pk_mul_f32 v[36:37], v[36:37], v[106:107]
	v_pk_mul_f32 v[34:35], v[34:35], v[104:105]
	v_pk_mul_f32 v[62:63], v[62:63], v[100:101]
	v_pk_mul_f32 v[58:59], v[58:59], v[96:97]
	v_pk_mul_f32 v[54:55], v[54:55], v[108:109]
	v_pk_mul_f32 v[64:65], v[64:65], v[102:103]
	v_pk_mul_f32 v[60:61], v[60:61], v[98:99]
	v_pk_mul_f32 v[56:57], v[56:57], v[110:111]
	v_pk_mul_f32 v[52:53], v[52:53], v[106:107]
	v_pk_mul_f32 v[50:51], v[50:51], v[104:105]
	v_pk_mul_f32 v[78:79], v[78:79], v[100:101]
	v_pk_mul_f32 v[74:75], v[74:75], v[96:97]
	v_pk_mul_f32 v[70:71], v[70:71], v[108:109]
	v_pk_mul_f32 v[80:81], v[80:81], v[102:103]
	v_pk_mul_f32 v[76:77], v[76:77], v[98:99]
	v_pk_mul_f32 v[72:73], v[72:73], v[110:111]
	v_pk_mul_f32 v[68:69], v[68:69], v[106:107]
	v_pk_mul_f32 v[66:67], v[66:67], v[104:105]
.LBB0_277:
	s_add_i32 s90, s90, 2
	s_waitcnt lgkmcnt(1)
	v_mfma_f32_32x32x16_bf16 v[98:113], v[90:93], v[86:89], v[146:161]
	v_exp_f32_e32 v130, v130
	v_exp_f32_e32 v131, v131
	ds_read_b128 v[180:183], v178 offset:4096
	v_exp_f32_e32 v132, v132
	v_exp_f32_e32 v133, v133
	v_exp_f32_e32 v134, v134
	v_exp_f32_e32 v135, v135
	v_mfma_f32_32x32x16_bf16 v[82:97], v[82:85], v[86:89], v[146:161]
	ds_read_b128 v[184:187], v178 offset:4608
	ds_read_b128 v[188:191], v248 offset:2048
	s_waitcnt lgkmcnt(3)
	v_mfma_f32_32x32x16_bf16 v[98:113], v[12:15], v[8:11], v[98:113]
	ds_read_b128 v[192:195], v178 offset:6144
	v_exp_f32_e32 v136, v136
	v_exp_f32_e32 v137, v137
	v_exp_f32_e32 v138, v138
	v_mfma_f32_32x32x16_bf16 v[82:97], v[4:7], v[8:11], v[82:97]
	ds_read_b128 v[12:15], v178 offset:6656
	ds_read_b128 v[196:199], v248 offset:3072
	v_exp_f32_e32 v139, v139
	v_exp_f32_e32 v140, v140
	v_exp_f32_e32 v141, v141
	s_waitcnt lgkmcnt(3)
	v_mfma_f32_32x32x16_bf16 v[98:113], v[180:183], v[188:191], v[98:113]
	v_exp_f32_e32 v142, v142
	ds_read_b64_tr_b16 v[4:5], v246 offset:40960
	ds_read_b64_tr_b16 v[6:7], v246 offset:41472
	v_exp_f32_e32 v143, v143
	v_exp_f32_e32 v144, v144
	v_cvt_pk_bf16_f32 v8, v130, v131
	v_cvt_pk_bf16_f32 v9, v132, v133
	v_cvt_pk_bf16_f32 v10, v134, v135
	v_cvt_pk_bf16_f32 v11, v136, v137
	v_mfma_f32_32x32x16_bf16 v[82:97], v[184:187], v[188:191], v[82:97]
	ds_read_b64_tr_b16 v[178:179], v246 offset:45056
	ds_read_b64_tr_b16 v[180:181], v246 offset:45568
	v_exp_f32_e32 v145, v145
	v_exp_f32_e32 v114, v114
	v_exp_f32_e32 v115, v115
	s_waitcnt lgkmcnt(4)
	v_mfma_f32_32x32x16_bf16 v[98:113], v[192:195], v[196:199], v[98:113]
	ds_read_b64_tr_b16 v[182:183], v246 offset:49152
	ds_read_b64_tr_b16 v[184:185], v246 offset:49664
	v_exp_f32_e32 v116, v116
	v_exp_f32_e32 v117, v117
	v_exp_f32_e32 v118, v118
	v_cvt_pk_bf16_f32 v186, v138, v139
	v_cvt_pk_bf16_f32 v187, v140, v141
	v_cvt_pk_bf16_f32 v188, v142, v143
	v_cvt_pk_bf16_f32 v189, v144, v145
	v_mfma_f32_32x32x16_bf16 v[82:97], v[12:15], v[196:199], v[82:97]
	ds_read_b64_tr_b16 v[190:191], v246 offset:53248
	ds_read_b64_tr_b16 v[192:193], v246 offset:53760
	v_exp_f32_e32 v119, v119
	v_exp_f32_e32 v120, v120
	v_exp_f32_e32 v121, v121
	s_waitcnt lgkmcnt(6)
	v_mfma_f32_32x32x16_bf16 v[18:33], v[8:11], v[4:7], v[18:33]
	ds_read_b64_tr_b16 v[12:13], v246 offset:41984
	ds_read_b64_tr_b16 v[14:15], v246 offset:42496
	v_add_f32_e32 v194, v130, v131
	v_exp_f32_e32 v122, v122
	v_exp_f32_e32 v123, v123
	v_add_f32_e32 v194, v132, v194
	v_add_f32_e32 v4, v133, v194
	v_add_f32_e32 v4, v134, v4
	v_add_f32_e32 v194, v135, v4
	s_waitcnt lgkmcnt(6)
	v_mfma_f32_32x32x16_bf16 v[34:49], v[8:11], v[178:181], v[34:49]
	ds_read_b64_tr_b16 v[4:5], v246 offset:46080
	ds_read_b64_tr_b16 v[6:7], v246 offset:46592
	v_exp_f32_e32 v124, v124
	v_exp_f32_e32 v125, v125
	v_add_f32_e32 v194, v136, v194
	v_add_f32_e32 v178, v137, v194
	v_add_f32_e32 v178, v138, v178
	v_add_f32_e32 v194, v139, v178
	s_waitcnt lgkmcnt(6)
	v_mfma_f32_32x32x16_bf16 v[50:65], v[8:11], v[182:185], v[50:65]
	ds_read_b64_tr_b16 v[178:179], v246 offset:50176
	ds_read_b64_tr_b16 v[180:181], v246 offset:50688
	v_exp_f32_e32 v126, v126
	v_exp_f32_e32 v127, v127
	v_add_f32_e32 v194, v140, v194
	v_add_f32_e32 v182, v141, v194
	v_add_f32_e32 v182, v142, v182
	v_add_f32_e32 v194, v143, v182
	s_waitcnt lgkmcnt(6)
	v_mfma_f32_32x32x16_bf16 v[66:81], v[8:11], v[190:193], v[66:81]
	ds_read_b64_tr_b16 v[182:183], v246 offset:54272
	ds_read_b64_tr_b16 v[184:185], v246 offset:54784
	v_exp_f32_e32 v128, v128
	v_exp_f32_e32 v129, v129
	v_add_f32_e32 v194, v144, v194
	v_add_f32_e32 v8, v145, v194
	v_add_f32_e32 v8, v114, v8
	v_add_f32_e32 v190, v115, v8
	s_waitcnt lgkmcnt(6)
	v_mfma_f32_32x32x16_bf16 v[18:33], v[186:189], v[12:15], v[18:33]
	ds_read_b64_tr_b16 v[8:9], v246 offset:43008
	ds_read_b64_tr_b16 v[10:11], v246 offset:43520
	v_add_f32_e32 v190, v116, v190
	v_add_f32_e32 v190, v117, v190
	v_add_f32_e32 v190, v118, v190
	v_add_f32_e32 v194, v119, v190
	v_cvt_pk_bf16_f32 v12, v114, v115
	v_cvt_pk_bf16_f32 v13, v116, v117
	v_cvt_pk_bf16_f32 v14, v118, v119
	v_cvt_pk_bf16_f32 v15, v120, v121
	s_waitcnt lgkmcnt(6)
; __device__ __forceinline__ int crow(int r,int hi){return (r&3)+8*(r>>2)+4*hi;}
; __device__ __forceinline__ float max3f(float a,float b,float c){float r;asm("v_max3_f32 %0, %1, %2, %3":"=v"(r):"v"(a),"v"(b),"v"(c));return r;}
; __device__ __forceinline__ float max2f(float a,float b){float r;asm("v_max_f32_e32 %0, %1, %2":"=v"(r):"v"(a),"v"(b));return r;}
;   #define PVG(i,PW,VF,NEXTI,X0,X1,Y0,Y1,EXTRA) do{ S.o[(i)&3]=MF32(__builtin_bit_cast(bf16x8,PW),VF,S.o[(i)&3]); if((NEXTI)<16){ VF=vfrag(vp,(NEXTI)<16?(NEXTI):0); } sa+=X0; sa+=X1; sa+=Y0; sa+=Y1; EXTRA; SB(); }while(0)
; template<int THRL,bool FIRST> __device__ __forceinline__ void decide(float rm,St&S,float*wsf,int r32,int hi){
;   if(FIRST){ S.mhat=rm; }
;   else if(__any(rm-S.mhat>(float)THRL)){
;     const float dl=__builtin_fmaxf(rm-S.mhat,0.f); S.mhat+=dl;
;     const float f=__builtin_amdgcn_exp2f(-dl); S.l_reg*=f; if(hi==0)wsf[r32]=f;
;     asm volatile("s_waitcnt lgkmcnt(0)":::"memory");
;     #pragma unroll
;     for(int r=0;r<16;++r){ const float fr=wsf[crow(r,hi)];
;       #pragma unroll
;       for(int d=0;d<4;++d)S.o[d][r]*=fr; }
; template<int THRL,bool FIRST> __device__ __forceinline__ void step_main(f32x16&p0,f32x16&p1,f32x16&n0,f32x16&n1,St&S,lds_cptr kpn,lds_cptr qp,lds_cptr vp,float*wsf,int r32,int hi,float&rm){
;     ...
;   PVG(8,pw2,vfa,12,0.f,0.f,0.f,0.f, do{ma=max3f(n0[0],n0[1],n1[0]);mb=max3f(n0[2],n0[3],n1[1]);PINAB();}while(0));
;   PVG(9,pw2,vfb,13,0.f,0.f,0.f,0.f, do{ma=max3f(ma,n1[2],n1[3]);mb=max3f(mb,n0[4],n0[5]);PINAB();}while(0));
;   PVG(10,pw2,vfc,14,0.f,0.f,0.f,0.f, do{ma=max3f(ma,n0[6],n0[7]);mb=max3f(mb,n1[4],n1[5]);PINAB();}while(0));
;   PVG(11,pw2,vfd,15,0.f,0.f,0.f,0.f, do{ma=max3f(ma,n1[6],n1[7]);mb=max3f(mb,n0[8],n0[9]);PINAB();}while(0));
;   PVG(12,pw3,vfa,16,0.f,0.f,0.f,0.f, do{ma=max3f(ma,n0[10],n0[11]);mb=max3f(mb,n1[8],n1[9]);PINAB();}while(0));
;   PVG(13,pw3,vfb,16,0.f,0.f,0.f,0.f, do{ma=max3f(ma,n1[10],n1[11]);mb=max3f(mb,n0[12],n0[13]);PINAB();}while(0));
;   PVG(14,pw3,vfc,16,0.f,0.f,0.f,0.f, do{ma=max3f(ma,n0[14],n0[15]);mb=max3f(mb,n1[12],n1[13]);PINAB();}while(0));
;   PVG(15,pw3,vfd,16,0.f,0.f,0.f,0.f, do{ma=max3f(ma,n1[14],n1[15]);ma=max2f(ma,mb);PINAB();}while(0));
;     ...
;   { auto rr=__builtin_amdgcn_permlane32_swap(__float_as_uint(ma),__float_as_uint(ma),false,false); rm=max2f(__uint_as_float(rr[0]),__uint_as_float(rr[1])); }
;     ...
;   S.l_reg+=sa;
; }
	v_mfma_f32_32x32x16_bf16 v[34:49], v[186:189], v[4:7], v[34:49]
	ds_read_b64_tr_b16 v[190:191], v246 offset:47104
	ds_read_b64_tr_b16 v[192:193], v246 offset:47616
	v_add_f32_e32 v194, v120, v194
	v_add_f32_e32 v194, v121, v194
	v_add_f32_e32 v194, v122, v194
	v_add_f32_e32 v198, v123, v194
	v_cvt_pk_bf16_f32 v4, v122, v123
	v_cvt_pk_bf16_f32 v5, v124, v125
	v_cvt_pk_bf16_f32 v6, v126, v127
	v_cvt_pk_bf16_f32 v7, v128, v129
	s_waitcnt lgkmcnt(6)
	v_mfma_f32_32x32x16_bf16 v[50:65], v[186:189], v[178:181], v[50:65]
	ds_read_b64_tr_b16 v[194:195], v246 offset:51200
	ds_read_b64_tr_b16 v[196:197], v246 offset:51712
	v_add_f32_e32 v198, v124, v198
	v_add_f32_e32 v198, v125, v198
	v_add_f32_e32 v198, v126, v198
	v_add_f32_e32 v198, v127, v198
	s_waitcnt lgkmcnt(6)
	v_mfma_f32_32x32x16_bf16 v[66:81], v[186:189], v[182:185], v[66:81]
	ds_read_b64_tr_b16 v[178:179], v246 offset:55296
	ds_read_b64_tr_b16 v[180:181], v246 offset:55808
	v_add_f32_e32 v198, v128, v198
	v_add_f32_e32 v198, v129, v198
	v_add_f32_e32 v198, 0, v198
	s_waitcnt lgkmcnt(6)
	v_mfma_f32_32x32x16_bf16 v[18:33], v[12:15], v[8:11], v[18:33]
	ds_read_b64_tr_b16 v[182:183], v246 offset:44032
	ds_read_b64_tr_b16 v[184:185], v246 offset:44544
	v_max3_f32 v186, v98, v99, v82
	v_max3_f32 v187, v100, v101, v83
	s_nop 0
	s_waitcnt lgkmcnt(6)
	v_mfma_f32_32x32x16_bf16 v[34:49], v[12:15], v[190:193], v[34:49]
	ds_read_b64_tr_b16 v[8:9], v246 offset:48128
	ds_read_b64_tr_b16 v[10:11], v246 offset:48640
	v_max3_f32 v199, v186, v84, v85
	v_max3_f32 v200, v187, v102, v103
	s_nop 0
	s_waitcnt lgkmcnt(6)
	v_mfma_f32_32x32x16_bf16 v[50:65], v[12:15], v[194:197], v[50:65]
	ds_read_b64_tr_b16 v[186:187], v246 offset:52224
	ds_read_b64_tr_b16 v[188:189], v246 offset:52736
	v_max3_f32 v199, v199, v104, v105
	v_max3_f32 v200, v200, v86, v87
	s_nop 0
	s_waitcnt lgkmcnt(6)
	v_mfma_f32_32x32x16_bf16 v[66:81], v[12:15], v[178:181], v[66:81]
	ds_read_b64_tr_b16 v[190:191], v246 offset:56320
	ds_read_b64_tr_b16 v[192:193], v246 offset:56832
	v_max3_f32 v194, v199, v88, v89
	v_max3_f32 v195, v200, v106, v107
	s_nop 0
	s_waitcnt lgkmcnt(6)
	v_mfma_f32_32x32x16_bf16 v[18:33], v[4:7], v[182:185], v[18:33]
	v_max3_f32 v12, v194, v108, v109
	v_max3_f32 v13, v195, v90, v91
	s_nop 0
	s_waitcnt lgkmcnt(4)
	v_mfma_f32_32x32x16_bf16 v[34:49], v[4:7], v[8:11], v[34:49]
	v_max3_f32 v12, v12, v92, v93
	v_max3_f32 v13, v13, v110, v111
	s_nop 0
	s_waitcnt lgkmcnt(2)
	v_mfma_f32_32x32x16_bf16 v[50:65], v[4:7], v[186:189], v[50:65]
	v_max3_f32 v8, v12, v112, v113
	v_max3_f32 v9, v13, v94, v95
	s_nop 0
	s_waitcnt lgkmcnt(0)
	v_mfma_f32_32x32x16_bf16 v[66:81], v[4:7], v[190:193], v[66:81]
	v_max3_f32 v8, v8, v96, v97
	s_nop 0
	v_max_f32_e32 v8, v8, v9
	s_nop 0
	s_add_i32 s4, s91, 0x2000
	s_cmpk_lg_i32 s91, 0x4000
	s_cselect_b32 s88, s4, 0
	s_add_u32 s58, s58, 0x180000
	s_addc_u32 s59, s59, 0
	s_add_u32 s50, s50, 0x180000
	s_waitcnt vmcnt(0) lgkmcnt(0)
	s_barrier
	s_addc_u32 s51, s51, 0
	v_mov_b32_e32 v4, v8
	v_add_f32_e32 v251, v17, v198
	s_cmp_lt_u32 s90, s89
	v_permlane32_swap_b32_e32 v8, v4
	v_max_f32_e32 v178, v8, v4
	s_cbranch_scc0 .LBB0_285
.LBB0_278:
	s_add_u32 s60, s58, 0xfff40000
	s_addc_u32 s61, s59, -1
	s_add_i32 s4, s88, s84
	s_mov_b32 s5, m0
	s_mov_b32 m0, s4
	s_nop 0
	global_load_lds_dwordx4 v252, s[60:61]
	s_mov_b32 m0, s5
	s_mov_b32 s4, m0
	s_mov_b32 m0, s79
	s_nop 0
	global_load_lds_dwordx4 v250, s[50:51]
	s_mov_b32 m0, s4
	s_add_u32 s60, s50, 0x80
	s_addc_u32 s61, s51, 0
	s_mov_b32 s4, m0
	s_mov_b32 m0, s41
	s_nop 0
	global_load_lds_dwordx4 v250, s[60:61]
	s_mov_b32 m0, s4
	v_add_u32_e32 v17, s91, v249
	ds_read_b128 v[122:125], v17
	ds_read_b128 v[114:117], v17 offset:512
	ds_read_b128 v[12:15], v17 offset:2048
	ds_read_b128 v[4:7], v17 offset:2560
	ds_read_b128 v[118:121], v248
	ds_read_b128 v[8:11], v248 offset:1024
	v_mov_b32_e32 v126, v178
	v_cmp_lt_f32_e32 vcc, s69, v126
	s_cbranch_vccz .LBB0_282
	v_max_f32_e32 v126, v126, v126
	v_max_f32_e32 v126, 0, v126
	v_exp_f32_e64 v127, -v126
	s_and_saveexec_b64 s[60:61], s[6:7]
	ds_write_b32 v16, v127
	s_or_b64 exec, exec, s[60:61]
	s_waitcnt lgkmcnt(0)
	v_add_u32_e32 v140, s78, v2
	ds_read_b128 v[128:131], v140 offset:64
	ds_read_b128 v[132:135], v140 offset:96
	ds_read_b128 v[136:139], v140
	ds_read_b128 v[140:143], v140 offset:32
	v_add_f32_e32 v247, v247, v126
	v_sub_f32_e32 v146, v146, v126
	v_sub_f32_e32 v147, v147, v126
	v_sub_f32_e32 v148, v148, v126
	v_sub_f32_e32 v149, v149, v126
	v_sub_f32_e32 v150, v150, v126
	v_sub_f32_e32 v151, v151, v126
	v_sub_f32_e32 v152, v152, v126
	v_sub_f32_e32 v153, v153, v126
	v_sub_f32_e32 v154, v154, v126
	v_sub_f32_e32 v155, v155, v126
	v_sub_f32_e32 v156, v156, v126
	v_sub_f32_e32 v157, v157, v126
	v_sub_f32_e32 v158, v158, v126
	v_sub_f32_e32 v159, v159, v126
	v_sub_f32_e32 v160, v160, v126
	v_sub_f32_e32 v161, v161, v126
	v_sub_f32_e32 v82, v82, v126
	v_sub_f32_e32 v83, v83, v126
	v_sub_f32_e32 v84, v84, v126
	v_sub_f32_e32 v85, v85, v126
	v_sub_f32_e32 v86, v86, v126
	v_sub_f32_e32 v87, v87, v126
	v_sub_f32_e32 v88, v88, v126
	v_sub_f32_e32 v89, v89, v126
	v_sub_f32_e32 v90, v90, v126
	v_sub_f32_e32 v91, v91, v126
	v_sub_f32_e32 v92, v92, v126
	v_sub_f32_e32 v93, v93, v126
	v_sub_f32_e32 v94, v94, v126
	v_sub_f32_e32 v95, v95, v126
	v_sub_f32_e32 v96, v96, v126
	v_sub_f32_e32 v97, v97, v126
	v_sub_f32_e32 v98, v98, v126
	v_sub_f32_e32 v99, v99, v126
	v_sub_f32_e32 v100, v100, v126
	v_sub_f32_e32 v101, v101, v126
	v_sub_f32_e32 v102, v102, v126
	v_sub_f32_e32 v103, v103, v126
	v_sub_f32_e32 v104, v104, v126
	v_sub_f32_e32 v105, v105, v126
	v_sub_f32_e32 v106, v106, v126
	v_sub_f32_e32 v107, v107, v126
	v_sub_f32_e32 v108, v108, v126
	v_sub_f32_e32 v109, v109, v126
	v_sub_f32_e32 v110, v110, v126
	v_sub_f32_e32 v111, v111, v126
	v_sub_f32_e32 v112, v112, v126
	v_sub_f32_e32 v113, v113, v126
	v_mul_f32_e32 v251, v251, v127
	s_waitcnt lgkmcnt(2)
; __device__ __forceinline__ int crow(int r,int hi){return (r&3)+8*(r>>2)+4*hi;}
; #define SB() __builtin_amdgcn_sched_barrier(0)
; #define MF32(a,b,c) __builtin_amdgcn_mfma_f32_32x32x16_bf16(a,b,c,0,0,0)
; #define EXP1(x) x=__builtin_amdgcn_exp2f((x)-mh_)
; __device__ __forceinline__ bf16x8 vfrag(lds_cptr vp,int i){ const s16x4 lo=vtr(vp+(i&3)*4096+(i>>2)*1024), hh=vtr(vp+(i&3)*4096+(i>>2)*1024+512); return (bf16x8){lo[0],lo[1],lo[2],lo[3],hh[0],hh[1],hh[2],hh[3]}; }
;   #define KF(i) LDSQ(kpn+((i)>>1)*2048+((i)&1)*512)
;   #define QF(d0) LDSQ(qp+(d0)*1024)
; template<int THRL,bool FIRST> __device__ __forceinline__ void decide(float rm,St&S,float*wsf,int r32,int hi){
;     ...
;     for(int r=0;r<16;++r){ const float fr=wsf[crow(r,hi)];
;       #pragma unroll
;       for(int d=0;d<4;++d)S.o[d][r]*=fr; }
; template<int THRL,bool FIRST> __device__ __forceinline__ void step_main(f32x16&p0,f32x16&p1,f32x16&n0,f32x16&n1,St&S,lds_cptr kpn,lds_cptr qp,lds_cptr vp,float*wsf,int r32,int hi,float&rm){
;     ...
;   bf16x8 ka=KF(0),kb=KF(1),kc=KF(2),kd=KF(3),qa=QF(0),qb=QF(1);
;   decide<THRL,FIRST>(rm,S,wsf,r32,hi);
;   u32x4 pw0,pw1,pw2,pw3; const float mh_=S.mhat; const f32x16 z=f32x16{};
;   SB();
;   n0=MF32(ka,qa,z); ka=KF(4); EXP1(p0[0]);EXP1(p0[1]);EXP1(p0[2]); SB();
;   n1=MF32(kb,qa,z); kb=KF(5); qa=QF(2); EXP1(p0[3]);EXP1(p0[4]);EXP1(p0[5]); SB();
;   n0=MF32(kc,qb,n0);   kc=KF(6); EXP1(p0[6]);EXP1(p0[7]);EXP1(p0[8]); SB();
;   n1=MF32(kd,qb,n1);   kd=KF(7); qb=QF(3); EXP1(p0[9]);EXP1(p0[10]);EXP1(p0[11]); SB();
;   bf16x8 vfa=vfrag(vp,0);
;   n0=MF32(ka,qa,n0);   EXP1(p0[12]);EXP1(p0[13]);EXP1(p0[14]); pw0=packw(p0,0); SB();
;   bf16x8 vfb=vfrag(vp,1);
;   n1=MF32(kb,qa,n1);   EXP1(p0[15]);EXP1(p1[0]);EXP1(p1[1]); SB();
;   bf16x8 vfc=vfrag(vp,2);
;   n0=MF32(kc,qb,n0);   EXP1(p1[2]);EXP1(p1[3]);EXP1(p1[4]); pw1=packw(p0,8); SB();
;   bf16x8 vfd=vfrag(vp,3);
;   n1=MF32(kd,qb,n1);   EXP1(p1[5]);EXP1(p1[6]);EXP1(p1[7]); SB();
;     ...
;   float sa=p0[0]+p0[1];
;     ...
;   PVG(0,pw0,vfa,4, p0[2],p0[3],p0[4],p0[5],   do{EXP1(p1[8]);EXP1(p1[9]);}while(0));
;   PVG(1,pw0,vfb,5, p0[6],p0[7],p0[8],p0[9], do{EXP1(p1[10]);EXP1(p1[11]);}while(0));
;   PVG(2,pw0,vfc,6, p0[10],p0[11],p0[12],p0[13], do{EXP1(p1[12]);EXP1(p1[13]);}while(0));
;   PVG(3,pw0,vfd,7, p0[14],p0[15],p1[0],p1[1],   do{EXP1(p1[14]);EXP1(p1[15]);}while(0));
	v_pk_mul_f32 v[30:31], v[30:31], v[132:133]
	v_pk_mul_f32 v[26:27], v[26:27], v[128:129]
	s_waitcnt lgkmcnt(0)
	v_pk_mul_f32 v[22:23], v[22:23], v[140:141]
	v_pk_mul_f32 v[32:33], v[32:33], v[134:135]
	v_pk_mul_f32 v[28:29], v[28:29], v[130:131]
	v_pk_mul_f32 v[24:25], v[24:25], v[142:143]
	v_pk_mul_f32 v[20:21], v[20:21], v[138:139]
	v_pk_mul_f32 v[18:19], v[18:19], v[136:137]
	v_pk_mul_f32 v[46:47], v[46:47], v[132:133]
	v_pk_mul_f32 v[42:43], v[42:43], v[128:129]
	v_pk_mul_f32 v[38:39], v[38:39], v[140:141]
	v_pk_mul_f32 v[48:49], v[48:49], v[134:135]
	v_pk_mul_f32 v[44:45], v[44:45], v[130:131]
	v_pk_mul_f32 v[40:41], v[40:41], v[142:143]
	v_pk_mul_f32 v[36:37], v[36:37], v[138:139]
	v_pk_mul_f32 v[34:35], v[34:35], v[136:137]
	v_pk_mul_f32 v[62:63], v[62:63], v[132:133]
	v_pk_mul_f32 v[58:59], v[58:59], v[128:129]
	v_pk_mul_f32 v[54:55], v[54:55], v[140:141]
	v_pk_mul_f32 v[64:65], v[64:65], v[134:135]
	v_pk_mul_f32 v[60:61], v[60:61], v[130:131]
	v_pk_mul_f32 v[56:57], v[56:57], v[142:143]
	v_pk_mul_f32 v[52:53], v[52:53], v[138:139]
	v_pk_mul_f32 v[50:51], v[50:51], v[136:137]
	v_pk_mul_f32 v[78:79], v[78:79], v[132:133]
	v_pk_mul_f32 v[74:75], v[74:75], v[128:129]
	v_pk_mul_f32 v[70:71], v[70:71], v[140:141]
	v_pk_mul_f32 v[80:81], v[80:81], v[134:135]
	v_pk_mul_f32 v[76:77], v[76:77], v[130:131]
	v_pk_mul_f32 v[72:73], v[72:73], v[142:143]
	v_pk_mul_f32 v[68:69], v[68:69], v[138:139]
	v_pk_mul_f32 v[66:67], v[66:67], v[136:137]
.LBB0_282:
	s_waitcnt lgkmcnt(1)
	v_mfma_f32_32x32x16_bf16 v[130:145], v[122:125], v[118:121], v[146:161]
	ds_read_b128 v[178:181], v17 offset:4096
	v_exp_f32_e32 v190, v98
	v_exp_f32_e32 v191, v99
	v_exp_f32_e32 v192, v100
	v_mfma_f32_32x32x16_bf16 v[114:129], v[114:117], v[118:121], v[146:161]
	ds_read_b128 v[182:185], v17 offset:4608
	ds_read_b128 v[186:189], v248 offset:2048
	v_exp_f32_e32 v193, v101
	v_exp_f32_e32 v194, v102
	v_exp_f32_e32 v195, v103
	s_waitcnt lgkmcnt(3)
	v_mfma_f32_32x32x16_bf16 v[130:145], v[12:15], v[8:11], v[130:145]
	ds_read_b128 v[98:101], v17 offset:6144
	v_exp_f32_e32 v196, v104
	v_exp_f32_e32 v197, v105
	v_exp_f32_e32 v198, v106
	v_mfma_f32_32x32x16_bf16 v[114:129], v[4:7], v[8:11], v[114:129]
	ds_read_b128 v[12:15], v17 offset:6656
	ds_read_b128 v[102:105], v248 offset:3072
	v_exp_f32_e32 v17, v107
	v_exp_f32_e32 v199, v108
	v_exp_f32_e32 v200, v109
	s_waitcnt lgkmcnt(3)
	v_mfma_f32_32x32x16_bf16 v[130:145], v[178:181], v[186:189], v[130:145]
	v_exp_f32_e32 v201, v110
	ds_read_b64_tr_b16 v[4:5], v246 offset:24576
	ds_read_b64_tr_b16 v[6:7], v246 offset:25088
	v_exp_f32_e32 v202, v111
	v_exp_f32_e32 v178, v112
	v_cvt_pk_bf16_f32 v8, v190, v191
	v_cvt_pk_bf16_f32 v9, v192, v193
	v_cvt_pk_bf16_f32 v10, v194, v195
	v_cvt_pk_bf16_f32 v11, v196, v197
	v_mfma_f32_32x32x16_bf16 v[114:129], v[182:185], v[186:189], v[114:129]
	ds_read_b64_tr_b16 v[106:107], v246 offset:28672
	ds_read_b64_tr_b16 v[108:109], v246 offset:29184
	v_exp_f32_e32 v180, v82
	v_exp_f32_e32 v179, v113
	v_exp_f32_e32 v181, v83
	s_waitcnt lgkmcnt(4)
	v_mfma_f32_32x32x16_bf16 v[130:145], v[98:101], v[102:105], v[130:145]
	ds_read_b64_tr_b16 v[110:111], v246 offset:32768
	ds_read_b64_tr_b16 v[112:113], v246 offset:33280
	v_exp_f32_e32 v182, v84
	v_exp_f32_e32 v183, v85
	v_exp_f32_e32 v184, v86
	v_cvt_pk_bf16_f32 v82, v198, v17
	v_cvt_pk_bf16_f32 v83, v199, v200
	v_cvt_pk_bf16_f32 v84, v201, v202
	v_cvt_pk_bf16_f32 v85, v178, v179
	v_mfma_f32_32x32x16_bf16 v[114:129], v[12:15], v[102:105], v[114:129]
	ds_read_b64_tr_b16 v[98:99], v246 offset:36864
	ds_read_b64_tr_b16 v[100:101], v246 offset:37376
	v_exp_f32_e32 v185, v87
	v_exp_f32_e32 v186, v88
	v_exp_f32_e32 v187, v89
	s_waitcnt lgkmcnt(6)
	v_mfma_f32_32x32x16_bf16 v[18:33], v[8:11], v[4:7], v[18:33]
	v_add_f32_e32 v86, v190, v191
	ds_read_b64_tr_b16 v[12:13], v246 offset:25600
	ds_read_b64_tr_b16 v[14:15], v246 offset:26112
	v_add_f32_e32 v86, v192, v86
	v_exp_f32_e32 v103, v91
	v_add_f32_e32 v4, v193, v86
	v_add_f32_e32 v4, v194, v4
	v_add_f32_e32 v86, v195, v4
	v_exp_f32_e32 v102, v90
	s_waitcnt lgkmcnt(6)
	v_mfma_f32_32x32x16_bf16 v[34:49], v[8:11], v[106:109], v[34:49]
	ds_read_b64_tr_b16 v[4:5], v246 offset:29696
	ds_read_b64_tr_b16 v[6:7], v246 offset:30208
	v_add_f32_e32 v86, v196, v86
	v_add_f32_e32 v86, v197, v86
	v_add_f32_e32 v86, v198, v86
	v_exp_f32_e32 v104, v92
	v_add_f32_e32 v17, v17, v86
	v_exp_f32_e32 v105, v93
	s_waitcnt lgkmcnt(6)
	v_mfma_f32_32x32x16_bf16 v[50:65], v[8:11], v[110:113], v[50:65]
	ds_read_b64_tr_b16 v[86:87], v246 offset:33792
	ds_read_b64_tr_b16 v[88:89], v246 offset:34304
	v_add_f32_e32 v17, v199, v17
	v_add_f32_e32 v17, v200, v17
	v_add_f32_e32 v17, v201, v17
	v_exp_f32_e32 v106, v94
	v_add_f32_e32 v17, v202, v17
	v_exp_f32_e32 v107, v95
	s_waitcnt lgkmcnt(6)
	v_mfma_f32_32x32x16_bf16 v[66:81], v[8:11], v[98:101], v[66:81]
	ds_read_b64_tr_b16 v[90:91], v246 offset:37888
	ds_read_b64_tr_b16 v[92:93], v246 offset:38400
	v_add_f32_e32 v17, v178, v17
	v_add_f32_e32 v8, v179, v17
	v_add_f32_e32 v8, v180, v8
	v_exp_f32_e32 v108, v96
	v_add_f32_e32 v17, v181, v8
	v_exp_f32_e32 v109, v97
	s_waitcnt lgkmcnt(6)
; #define EXP1(x) x=__builtin_amdgcn_exp2f((x)-mh_)
; template<int THRL,bool FIRST> __device__ __forceinline__ void step_main(f32x16&p0,f32x16&p1,f32x16&n0,f32x16&n1,St&S,lds_cptr kpn,lds_cptr qp,lds_cptr vp,float*wsf,int r32,int hi,float&rm){
;     ...
;   PVG(0,pw0,vfa,4, p0[2],p0[3],p0[4],p0[5],   do{EXP1(p1[8]);EXP1(p1[9]);}while(0));
;   PVG(1,pw0,vfb,5, p0[6],p0[7],p0[8],p0[9], do{EXP1(p1[10]);EXP1(p1[11]);}while(0));
;   PVG(2,pw0,vfc,6, p0[10],p0[11],p0[12],p0[13], do{EXP1(p1[12]);EXP1(p1[13]);}while(0));
;   PVG(3,pw0,vfd,7, p0[14],p0[15],p1[0],p1[1],   do{EXP1(p1[14]);EXP1(p1[15]);}while(0));
;   PVG(4,pw1,vfa,8, p1[2],p1[3],p1[4],p1[5],   pw2=packw(p1,0));
;   PVG(5,pw1,vfb,9, p1[6],p1[7],p1[8],p1[9], pw3=packw(p1,8));
;   PVG(6,pw1,vfc,10, p1[10],p1[11],p1[12],p1[13], do{}while(0));
;   PVG(7,pw1,vfd,11, p1[14],p1[15],0.f,0.f, do{}while(0));
;   float ma,mb;
;     ...
;   PVG(8,pw2,vfa,12,0.f,0.f,0.f,0.f, do{ma=max3f(n0[0],n0[1],n1[0]);mb=max3f(n0[2],n0[3],n1[1]);PINAB();}while(0));
;   PVG(9,pw2,vfb,13,0.f,0.f,0.f,0.f, do{ma=max3f(ma,n1[2],n1[3]);mb=max3f(mb,n0[4],n0[5]);PINAB();}while(0));
;   PVG(10,pw2,vfc,14,0.f,0.f,0.f,0.f, do{ma=max3f(ma,n0[6],n0[7]);mb=max3f(mb,n1[4],n1[5]);PINAB();}while(0));
;   PVG(11,pw2,vfd,15,0.f,0.f,0.f,0.f, do{ma=max3f(ma,n1[6],n1[7]);mb=max3f(mb,n0[8],n0[9]);PINAB();}while(0));
;   PVG(12,pw3,vfa,16,0.f,0.f,0.f,0.f, do{ma=max3f(ma,n0[10],n0[11]);mb=max3f(mb,n1[8],n1[9]);PINAB();}while(0));
;   PVG(13,pw3,vfb,16,0.f,0.f,0.f,0.f, do{ma=max3f(ma,n1[10],n1[11]);mb=max3f(mb,n0[12],n0[13]);PINAB();}while(0));
;   PVG(14,pw3,vfc,16,0.f,0.f,0.f,0.f, do{ma=max3f(ma,n0[14],n0[15]);mb=max3f(mb,n1[12],n1[13]);PINAB();}while(0));
;   PVG(15,pw3,vfd,16,0.f,0.f,0.f,0.f, do{ma=max3f(ma,n1[14],n1[15]);ma=max2f(ma,mb);PINAB();}while(0));
;     ...
;   { auto rr=__builtin_amdgcn_permlane32_swap(__float_as_uint(ma),__float_as_uint(ma),false,false); rm=max2f(__uint_as_float(rr[0]),__uint_as_float(rr[1])); }
;     ...
;   S.l_reg+=sa;
; }
; template<int THRL> __device__ __forceinline__ void unit(int qb,const bf16*Q,const bf16*K,const bf16*V,bf16*O,char*shm){
;     ...
;       DMA_K(t+2,ks2); DMA_V(t+1,VBUF);
;       step_main<THRL,false>(pA0,pA1,pB0,pB1,S,kp0+ks1,qp,vp0,wsf,r32,hi,rm); A128_WAITBAR(); ROT();
;       DMA_K(t+3,ks2); DMA_V(t+2,0);
;       step_main<THRL,false>(pB0,pB1,pA0,pA1,S,kp0+ks1,qp,vp0+VBUF,wsf,r32,hi,rm); A128_WAITBAR(); ROT();
	v_mfma_f32_32x32x16_bf16 v[18:33], v[82:85], v[12:15], v[18:33]
	ds_read_b64_tr_b16 v[8:9], v246 offset:26624
	ds_read_b64_tr_b16 v[10:11], v246 offset:27136
	v_add_f32_e32 v17, v182, v17
	v_add_f32_e32 v17, v183, v17
	v_add_f32_e32 v17, v184, v17
	v_add_f32_e32 v17, v185, v17
	v_cvt_pk_bf16_f32 v12, v180, v181
	v_cvt_pk_bf16_f32 v13, v182, v183
	v_cvt_pk_bf16_f32 v14, v184, v185
	v_cvt_pk_bf16_f32 v15, v186, v187
	s_waitcnt lgkmcnt(6)
	v_mfma_f32_32x32x16_bf16 v[34:49], v[82:85], v[4:7], v[34:49]
	ds_read_b64_tr_b16 v[94:95], v246 offset:30720
	ds_read_b64_tr_b16 v[96:97], v246 offset:31232
	v_add_f32_e32 v17, v186, v17
	v_add_f32_e32 v17, v187, v17
	v_add_f32_e32 v17, v102, v17
	v_add_f32_e32 v17, v103, v17
	v_cvt_pk_bf16_f32 v4, v102, v103
	v_cvt_pk_bf16_f32 v5, v104, v105
	v_cvt_pk_bf16_f32 v6, v106, v107
	v_cvt_pk_bf16_f32 v7, v108, v109
	s_waitcnt lgkmcnt(6)
	v_mfma_f32_32x32x16_bf16 v[50:65], v[82:85], v[86:89], v[50:65]
	ds_read_b64_tr_b16 v[98:99], v246 offset:34816
	ds_read_b64_tr_b16 v[100:101], v246 offset:35328
	v_add_f32_e32 v17, v104, v17
	v_add_f32_e32 v17, v105, v17
	v_add_f32_e32 v17, v106, v17
	v_add_f32_e32 v17, v107, v17
	s_waitcnt lgkmcnt(6)
	v_mfma_f32_32x32x16_bf16 v[66:81], v[82:85], v[90:93], v[66:81]
	ds_read_b64_tr_b16 v[86:87], v246 offset:38912
	ds_read_b64_tr_b16 v[88:89], v246 offset:39424
	v_add_f32_e32 v17, v108, v17
	v_add_f32_e32 v17, v109, v17
	v_add_f32_e32 v17, 0, v17
	s_waitcnt lgkmcnt(6)
	v_mfma_f32_32x32x16_bf16 v[18:33], v[12:15], v[8:11], v[18:33]
	ds_read_b64_tr_b16 v[82:83], v246 offset:27648
	ds_read_b64_tr_b16 v[84:85], v246 offset:28160
	v_max3_f32 v90, v130, v131, v114
	v_max3_f32 v91, v132, v133, v115
	s_nop 0
	s_waitcnt lgkmcnt(6)
	v_mfma_f32_32x32x16_bf16 v[34:49], v[12:15], v[94:97], v[34:49]
	ds_read_b64_tr_b16 v[8:9], v246 offset:31744
	ds_read_b64_tr_b16 v[10:11], v246 offset:32256
	v_max3_f32 v102, v90, v116, v117
	v_max3_f32 v103, v91, v134, v135
	s_nop 0
	s_waitcnt lgkmcnt(6)
	v_mfma_f32_32x32x16_bf16 v[50:65], v[12:15], v[98:101], v[50:65]
	ds_read_b64_tr_b16 v[90:91], v246 offset:35840
	ds_read_b64_tr_b16 v[92:93], v246 offset:36352
	v_max3_f32 v102, v102, v136, v137
	v_max3_f32 v103, v103, v118, v119
	s_nop 0
	s_waitcnt lgkmcnt(6)
	v_mfma_f32_32x32x16_bf16 v[66:81], v[12:15], v[86:89], v[66:81]
	ds_read_b64_tr_b16 v[94:95], v246 offset:39936
	ds_read_b64_tr_b16 v[96:97], v246 offset:40448
	v_max3_f32 v98, v102, v120, v121
	v_max3_f32 v99, v103, v138, v139
	s_nop 0
	s_waitcnt lgkmcnt(6)
	v_mfma_f32_32x32x16_bf16 v[18:33], v[4:7], v[82:85], v[18:33]
	v_max3_f32 v12, v98, v140, v141
	v_max3_f32 v13, v99, v122, v123
	s_nop 0
	s_waitcnt lgkmcnt(4)
	v_mfma_f32_32x32x16_bf16 v[34:49], v[4:7], v[8:11], v[34:49]
	v_max3_f32 v12, v12, v124, v125
	v_max3_f32 v13, v13, v142, v143
	s_nop 0
	s_waitcnt lgkmcnt(2)
	v_mfma_f32_32x32x16_bf16 v[50:65], v[4:7], v[90:93], v[50:65]
	v_max3_f32 v8, v12, v144, v145
	v_max3_f32 v9, v13, v126, v127
	s_nop 0
	s_waitcnt lgkmcnt(0)
	v_mfma_f32_32x32x16_bf16 v[66:81], v[4:7], v[94:97], v[66:81]
	v_max3_f32 v8, v8, v128, v129
	s_nop 0
	v_max_f32_e32 v8, v8, v9
	s_nop 0
	s_add_i32 s4, s88, 0x2000
	s_cmpk_lg_i32 s88, 0x4000
	s_cselect_b32 s91, s4, 0
	s_add_i32 s4, s91, s84
	s_waitcnt vmcnt(0) lgkmcnt(0)
	s_barrier
	s_add_u32 s60, s50, 0xc0000
	s_mov_b32 s5, m0
	s_mov_b32 m0, s4
	s_nop 0
	global_load_lds_dwordx4 v252, s[58:59]
	s_mov_b32 m0, s5
	s_addc_u32 s61, s51, 0
	v_mov_b32_e32 v4, v8
	s_mov_b32 s4, m0
	s_mov_b32 m0, s80
	s_nop 0
	global_load_lds_dwordx4 v250, s[60:61]
	s_mov_b32 m0, s4
	s_add_u32 s60, s50, 0xc0080
	s_nop 0
	v_permlane32_swap_b32_e32 v8, v4
	s_addc_u32 s61, s51, 0
	s_mov_b32 s4, m0
	s_mov_b32 m0, s83
	s_nop 0
	global_load_lds_dwordx4 v250, s[60:61]
	s_mov_b32 m0, s4
	v_add_u32_e32 v178, s88, v249
	v_max_f32_e32 v94, v8, v4
	ds_read_b128 v[90:93], v178
	ds_read_b128 v[82:85], v178 offset:512
	ds_read_b128 v[12:15], v178 offset:2048
	ds_read_b128 v[4:7], v178 offset:2560
	ds_read_b128 v[86:89], v248
	ds_read_b128 v[8:11], v248 offset:1024
	v_add_f32_e32 v17, v251, v17
	v_cmp_lt_f32_e32 vcc, s69, v94
	s_cbranch_vccz .LBB0_277
	v_max_f32_e32 v94, v94, v94
	v_max_f32_e32 v94, 0, v94
	v_exp_f32_e64 v95, -v94
	s_and_saveexec_b64 s[60:61], s[6:7]
	s_cbranch_execz .LBB0_276
	ds_write_b32 v16, v95
	s_branch .LBB0_276
.LBB0_285:
	v_add_f32_e32 v82, v82, v247
	v_add_f32_e32 v83, v83, v247
	v_add_f32_e32 v84, v84, v247
	v_add_f32_e32 v85, v85, v247
	v_add_f32_e32 v86, v86, v247
	v_add_f32_e32 v87, v87, v247
	v_add_f32_e32 v88, v88, v247
	v_add_f32_e32 v89, v89, v247
	v_add_f32_e32 v90, v90, v247
	v_add_f32_e32 v91, v91, v247
	v_add_f32_e32 v92, v92, v247
	v_add_f32_e32 v93, v93, v247
	v_add_f32_e32 v94, v94, v247
	v_add_f32_e32 v95, v95, v247
	v_add_f32_e32 v96, v96, v247
	v_add_f32_e32 v97, v97, v247
	v_add_f32_e32 v98, v98, v247
	v_add_f32_e32 v99, v99, v247
	v_add_f32_e32 v100, v100, v247
	v_add_f32_e32 v101, v101, v247
	v_add_f32_e32 v102, v102, v247
	v_add_f32_e32 v103, v103, v247
	v_add_f32_e32 v104, v104, v247
	v_add_f32_e32 v105, v105, v247
	v_add_f32_e32 v106, v106, v247
	v_add_f32_e32 v107, v107, v247
	v_add_f32_e32 v108, v108, v247
	v_add_f32_e32 v109, v109, v247
	v_add_f32_e32 v110, v110, v247
	v_add_f32_e32 v111, v111, v247
	v_add_f32_e32 v112, v112, v247
	v_add_f32_e32 v113, v113, v247
	v_add_f32_e32 v178, v178, v247
	s_branch .LBB0_287

; __device__ __forceinline__ float max3f(float a,float b,float c){float r;asm("v_max3_f32 %0, %1, %2, %3":"=v"(r):"v"(a),"v"(b),"v"(c));return r;}
; #define SB() __builtin_amdgcn_sched_barrier(0)
; #define EXP1(x) x=__builtin_amdgcn_exp2f((x)-mh_)
; template<int THRL,bool FIRST> __device__ __forceinline__ void step_main(f32x16&p0,f32x16&p1,f32x16&n0,f32x16&n1,St&S,lds_cptr kpn,lds_cptr qp,lds_cptr vp,float*wsf,int r32,int hi,float&rm){
;     ...
;   bf16x8 ka=KF(0),kb=KF(1),kc=KF(2),kd=KF(3),qa=QF(0),qb=QF(1);
;   decide<THRL,FIRST>(rm,S,wsf,r32,hi);
;   u32x4 pw0,pw1,pw2,pw3; const float mh_=S.mhat; const f32x16 z=f32x16{};
;   SB();
;   n0=MF32(ka,qa,z); ka=KF(4); EXP1(p0[0]);EXP1(p0[1]);EXP1(p0[2]); SB();
;   n1=MF32(kb,qa,z); kb=KF(5); qa=QF(2); EXP1(p0[3]);EXP1(p0[4]);EXP1(p0[5]); SB();
;   n0=MF32(kc,qb,n0);   kc=KF(6); EXP1(p0[6]);EXP1(p0[7]);EXP1(p0[8]); SB();
;   n1=MF32(kd,qb,n1);   kd=KF(7); qb=QF(3); EXP1(p0[9]);EXP1(p0[10]);EXP1(p0[11]); SB();
;   bf16x8 vfa=vfrag(vp,0);
;   n0=MF32(ka,qa,n0);   EXP1(p0[12]);EXP1(p0[13]);EXP1(p0[14]); pw0=packw(p0,0); SB();
;   bf16x8 vfb=vfrag(vp,1);
;   n1=MF32(kb,qa,n1);   EXP1(p0[15]);EXP1(p1[0]);EXP1(p1[1]); SB();
;   bf16x8 vfc=vfrag(vp,2);
;   n0=MF32(kc,qb,n0);   EXP1(p1[2]);EXP1(p1[3]);EXP1(p1[4]); pw1=packw(p0,8); SB();
;   bf16x8 vfd=vfrag(vp,3);
;   n1=MF32(kd,qb,n1);   EXP1(p1[5]);EXP1(p1[6]);EXP1(p1[7]); SB();
;     ...
;   float sa=p0[0]+p0[1];
;     ...
;   PVG(0,pw0,vfa,4, p0[2],p0[3],p0[4],p0[5],   do{EXP1(p1[8]);EXP1(p1[9]);}while(0));
;   PVG(1,pw0,vfb,5, p0[6],p0[7],p0[8],p0[9], do{EXP1(p1[10]);EXP1(p1[11]);}while(0));
;   PVG(2,pw0,vfc,6, p0[10],p0[11],p0[12],p0[13], do{EXP1(p1[12]);EXP1(p1[13]);}while(0));
;   PVG(3,pw0,vfd,7, p0[14],p0[15],p1[0],p1[1],   do{EXP1(p1[14]);EXP1(p1[15]);}while(0));
;   PVG(4,pw1,vfa,8, p1[2],p1[3],p1[4],p1[5],   pw2=packw(p1,0));
;   PVG(5,pw1,vfb,9, p1[6],p1[7],p1[8],p1[9], pw3=packw(p1,8));
;   PVG(6,pw1,vfc,10, p1[10],p1[11],p1[12],p1[13], do{}while(0));
;   PVG(7,pw1,vfd,11, p1[14],p1[15],0.f,0.f, do{}while(0));
;   float ma,mb;
;     ...
;   PVG(8,pw2,vfa,12,0.f,0.f,0.f,0.f, do{ma=max3f(n0[0],n0[1],n1[0]);mb=max3f(n0[2],n0[3],n1[1]);PINAB();}while(0));
;   PVG(9,pw2,vfb,13,0.f,0.f,0.f,0.f, do{ma=max3f(ma,n1[2],n1[3]);mb=max3f(mb,n0[4],n0[5]);PINAB();}while(0));
;   PVG(10,pw2,vfc,14,0.f,0.f,0.f,0.f, do{ma=max3f(ma,n0[6],n0[7]);mb=max3f(mb,n1[4],n1[5]);PINAB();}while(0));
.LBB0_433:
	s_waitcnt lgkmcnt(1)
	v_mfma_f32_32x32x16_bf16 v[98:113], v[218:221], v[214:217], 0
	ds_read_b128 v[178:181], v249 offset:20480
	v_sub_f32_e32 v82, v131, v247
	v_sub_f32_e32 v17, v130, v247
	v_exp_f32_e32 v190, v82
	v_sub_f32_e32 v82, v132, v247
	v_exp_f32_e32 v17, v17
	v_exp_f32_e32 v191, v82
	v_sub_f32_e32 v82, v133, v247
	v_exp_f32_e32 v192, v82
	v_sub_f32_e32 v82, v134, v247
	v_exp_f32_e32 v193, v82
	v_sub_f32_e32 v82, v135, v247
	v_exp_f32_e32 v194, v82
	v_mfma_f32_32x32x16_bf16 v[82:97], v[210:213], v[214:217], 0
	ds_read_b128 v[182:185], v249 offset:20992
	ds_read_b128 v[186:189], v248 offset:2048
	s_waitcnt lgkmcnt(3)
	v_mfma_f32_32x32x16_bf16 v[98:113], v[12:15], v[8:11], v[98:113]
	ds_read_b128 v[130:133], v249 offset:22528
	v_sub_f32_e32 v134, v136, v247
	v_exp_f32_e32 v195, v134
	v_sub_f32_e32 v134, v137, v247
	v_exp_f32_e32 v196, v134
	v_sub_f32_e32 v134, v138, v247
	v_exp_f32_e32 v197, v134
	v_mfma_f32_32x32x16_bf16 v[82:97], v[4:7], v[8:11], v[82:97]
	ds_read_b128 v[12:15], v249 offset:23040
	ds_read_b128 v[134:137], v248 offset:3072
	v_sub_f32_e32 v138, v139, v247
	v_exp_f32_e32 v198, v138
	v_sub_f32_e32 v138, v140, v247
	v_exp_f32_e32 v199, v138
	v_sub_f32_e32 v138, v141, v247
	v_exp_f32_e32 v200, v138
	s_waitcnt lgkmcnt(3)
	v_mfma_f32_32x32x16_bf16 v[98:113], v[178:181], v[186:189], v[98:113]
	ds_read_b64_tr_b16 v[4:5], v246 offset:40960
	ds_read_b64_tr_b16 v[6:7], v246 offset:41472
	v_sub_f32_e32 v8, v142, v247
	v_exp_f32_e32 v201, v8
	v_sub_f32_e32 v8, v143, v247
	v_exp_f32_e32 v202, v8
	v_sub_f32_e32 v8, v144, v247
	v_exp_f32_e32 v179, v8
	v_cvt_pk_bf16_f32 v8, v17, v190
	v_cvt_pk_bf16_f32 v9, v191, v192
	v_cvt_pk_bf16_f32 v10, v193, v194
	v_cvt_pk_bf16_f32 v11, v195, v196
	v_mfma_f32_32x32x16_bf16 v[82:97], v[182:185], v[186:189], v[82:97]
	ds_read_b64_tr_b16 v[138:139], v246 offset:45056
	ds_read_b64_tr_b16 v[140:141], v246 offset:45568
	v_sub_f32_e32 v114, v114, v247
	v_sub_f32_e32 v142, v145, v247
	v_exp_f32_e32 v181, v114
	v_sub_f32_e32 v114, v115, v247
	v_exp_f32_e32 v180, v142
	v_exp_f32_e32 v203, v114
	s_waitcnt lgkmcnt(4)
	v_mfma_f32_32x32x16_bf16 v[98:113], v[130:133], v[134:137], v[98:113]
	ds_read_b64_tr_b16 v[142:143], v246 offset:49152
	ds_read_b64_tr_b16 v[144:145], v246 offset:49664
	v_sub_f32_e32 v114, v116, v247
	v_exp_f32_e32 v182, v114
	v_sub_f32_e32 v114, v117, v247
	v_exp_f32_e32 v183, v114
	v_sub_f32_e32 v114, v118, v247
	v_exp_f32_e32 v184, v114
	v_cvt_pk_bf16_f32 v114, v197, v198
	v_cvt_pk_bf16_f32 v115, v199, v200
	v_cvt_pk_bf16_f32 v116, v201, v202
	v_cvt_pk_bf16_f32 v117, v179, v180
	v_mfma_f32_32x32x16_bf16 v[82:97], v[12:15], v[134:137], v[82:97]
	ds_read_b64_tr_b16 v[130:131], v246 offset:53248
	ds_read_b64_tr_b16 v[132:133], v246 offset:53760
	v_sub_f32_e32 v118, v119, v247
	v_exp_f32_e32 v185, v118
	v_sub_f32_e32 v118, v120, v247
	v_exp_f32_e32 v186, v118
	v_sub_f32_e32 v118, v121, v247
	v_exp_f32_e32 v187, v118
	s_waitcnt lgkmcnt(6)
	v_mfma_f32_32x32x16_bf16 v[18:33], v[8:11], v[4:7], v[18:33]
	ds_read_b64_tr_b16 v[12:13], v246 offset:41984
	ds_read_b64_tr_b16 v[14:15], v246 offset:42496
	v_sub_f32_e32 v118, v122, v247
	v_exp_f32_e32 v134, v118
	v_sub_f32_e32 v118, v123, v247
	v_exp_f32_e32 v135, v118
	s_waitcnt lgkmcnt(6)
	v_mfma_f32_32x32x16_bf16 v[34:49], v[8:11], v[138:141], v[34:49]
	ds_read_b64_tr_b16 v[4:5], v246 offset:46080
	ds_read_b64_tr_b16 v[6:7], v246 offset:46592
	v_sub_f32_e32 v118, v124, v247
	v_exp_f32_e32 v136, v118
	v_sub_f32_e32 v118, v125, v247
	v_exp_f32_e32 v137, v118
	s_waitcnt lgkmcnt(6)
	v_mfma_f32_32x32x16_bf16 v[50:65], v[8:11], v[142:145], v[50:65]
	ds_read_b64_tr_b16 v[118:119], v246 offset:50176
	ds_read_b64_tr_b16 v[120:121], v246 offset:50688
	v_sub_f32_e32 v122, v126, v247
	v_exp_f32_e32 v138, v122
	v_sub_f32_e32 v122, v127, v247
	v_exp_f32_e32 v139, v122
	s_waitcnt lgkmcnt(6)
	v_mfma_f32_32x32x16_bf16 v[66:81], v[8:11], v[130:133], v[66:81]
	ds_read_b64_tr_b16 v[122:123], v246 offset:54272
	ds_read_b64_tr_b16 v[124:125], v246 offset:54784
	v_sub_f32_e32 v126, v128, v247
	v_exp_f32_e32 v140, v126
	v_sub_f32_e32 v126, v129, v247
	v_exp_f32_e32 v141, v126
	s_waitcnt lgkmcnt(6)
	v_mfma_f32_32x32x16_bf16 v[18:33], v[114:117], v[12:15], v[18:33]
	ds_read_b64_tr_b16 v[8:9], v246 offset:43008
	ds_read_b64_tr_b16 v[10:11], v246 offset:43520
	v_cvt_pk_bf16_f32 v126, v181, v203
	v_cvt_pk_bf16_f32 v127, v182, v183
	v_cvt_pk_bf16_f32 v128, v184, v185
	v_cvt_pk_bf16_f32 v129, v186, v187
	s_waitcnt lgkmcnt(6)
	v_mfma_f32_32x32x16_bf16 v[34:49], v[114:117], v[4:7], v[34:49]
	ds_read_b64_tr_b16 v[12:13], v246 offset:47104
	ds_read_b64_tr_b16 v[14:15], v246 offset:47616
	v_cvt_pk_bf16_f32 v130, v134, v135
	v_cvt_pk_bf16_f32 v131, v136, v137
	v_cvt_pk_bf16_f32 v132, v138, v139
	v_cvt_pk_bf16_f32 v133, v140, v141
	s_waitcnt lgkmcnt(6)
	v_mfma_f32_32x32x16_bf16 v[50:65], v[114:117], v[118:121], v[50:65]
	ds_read_b64_tr_b16 v[4:5], v246 offset:51200
	ds_read_b64_tr_b16 v[6:7], v246 offset:51712
	s_waitcnt lgkmcnt(6)
	v_mfma_f32_32x32x16_bf16 v[66:81], v[114:117], v[122:125], v[66:81]
	ds_read_b64_tr_b16 v[118:119], v246 offset:55296
	ds_read_b64_tr_b16 v[120:121], v246 offset:55808
	s_waitcnt lgkmcnt(6)
	v_mfma_f32_32x32x16_bf16 v[18:33], v[126:129], v[8:11], v[18:33]
	ds_read_b64_tr_b16 v[114:115], v246 offset:44032
	ds_read_b64_tr_b16 v[116:117], v246 offset:44544
	v_max3_f32 v122, v98, v99, v82
	v_max3_f32 v123, v100, v101, v83
	s_nop 0
	s_waitcnt lgkmcnt(6)
	v_mfma_f32_32x32x16_bf16 v[34:49], v[126:129], v[12:15], v[34:49]
	ds_read_b64_tr_b16 v[8:9], v246 offset:48128
	ds_read_b64_tr_b16 v[10:11], v246 offset:48640
	v_max3_f32 v122, v122, v84, v85
	v_max3_f32 v123, v123, v102, v103
	s_nop 0
	s_waitcnt lgkmcnt(6)
; __device__ __forceinline__ int crow(int r,int hi){return (r&3)+8*(r>>2)+4*hi;}
; __device__ __forceinline__ float max3f(float a,float b,float c){float r;asm("v_max3_f32 %0, %1, %2, %3":"=v"(r):"v"(a),"v"(b),"v"(c));return r;}
; __device__ __forceinline__ float max2f(float a,float b){float r;asm("v_max_f32_e32 %0, %1, %2":"=v"(r):"v"(a),"v"(b));return r;}
;   #define PVG(i,PW,VF,NEXTI,X0,X1,Y0,Y1,EXTRA) do{ S.o[(i)&3]=MF32(__builtin_bit_cast(bf16x8,PW),VF,S.o[(i)&3]); if((NEXTI)<16){ VF=vfrag(vp,(NEXTI)<16?(NEXTI):0); } sa+=X0; sa+=X1; sa+=Y0; sa+=Y1; EXTRA; SB(); }while(0)
; template<int THRL,bool FIRST> __device__ __forceinline__ void decide(float rm,St&S,float*wsf,int r32,int hi){
;     ...
;   else if(__any(rm-S.mhat>(float)THRL)){
;     const float dl=__builtin_fmaxf(rm-S.mhat,0.f); S.mhat+=dl;
;     const float f=__builtin_amdgcn_exp2f(-dl); S.l_reg*=f; if(hi==0)wsf[r32]=f;
;     asm volatile("s_waitcnt lgkmcnt(0)":::"memory");
;     #pragma unroll
;     for(int r=0;r<16;++r){ const float fr=wsf[crow(r,hi)];
;       #pragma unroll
;       for(int d=0;d<4;++d)S.o[d][r]*=fr; }
; template<int THRL,bool FIRST> __device__ __forceinline__ void step_main(f32x16&p0,f32x16&p1,f32x16&n0,f32x16&n1,St&S,lds_cptr kpn,lds_cptr qp,lds_cptr vp,float*wsf,int r32,int hi,float&rm){
;     ...
;   PVG(8,pw2,vfa,12,0.f,0.f,0.f,0.f, do{ma=max3f(n0[0],n0[1],n1[0]);mb=max3f(n0[2],n0[3],n1[1]);PINAB();}while(0));
;   PVG(9,pw2,vfb,13,0.f,0.f,0.f,0.f, do{ma=max3f(ma,n1[2],n1[3]);mb=max3f(mb,n0[4],n0[5]);PINAB();}while(0));
;   PVG(10,pw2,vfc,14,0.f,0.f,0.f,0.f, do{ma=max3f(ma,n0[6],n0[7]);mb=max3f(mb,n1[4],n1[5]);PINAB();}while(0));
;   PVG(11,pw2,vfd,15,0.f,0.f,0.f,0.f, do{ma=max3f(ma,n1[6],n1[7]);mb=max3f(mb,n0[8],n0[9]);PINAB();}while(0));
;   PVG(12,pw3,vfa,16,0.f,0.f,0.f,0.f, do{ma=max3f(ma,n0[10],n0[11]);mb=max3f(mb,n1[8],n1[9]);PINAB();}while(0));
;   PVG(13,pw3,vfb,16,0.f,0.f,0.f,0.f, do{ma=max3f(ma,n1[10],n1[11]);mb=max3f(mb,n0[12],n0[13]);PINAB();}while(0));
;   PVG(14,pw3,vfc,16,0.f,0.f,0.f,0.f, do{ma=max3f(ma,n0[14],n0[15]);mb=max3f(mb,n1[12],n1[13]);PINAB();}while(0));
;   PVG(15,pw3,vfd,16,0.f,0.f,0.f,0.f, do{ma=max3f(ma,n1[14],n1[15]);ma=max2f(ma,mb);PINAB();}while(0));
;     ...
;   { auto rr=__builtin_amdgcn_permlane32_swap(__float_as_uint(ma),__float_as_uint(ma),false,false); rm=max2f(__uint_as_float(rr[0]),__uint_as_float(rr[1])); }
;     ...
;   S.l_reg+=sa;
	v_mfma_f32_32x32x16_bf16 v[50:65], v[126:129], v[4:7], v[50:65]
	ds_read_b64_tr_b16 v[12:13], v246 offset:52224
	ds_read_b64_tr_b16 v[14:15], v246 offset:52736
	v_max3_f32 v122, v122, v104, v105
	v_max3_f32 v123, v123, v86, v87
	s_nop 0
	s_waitcnt lgkmcnt(6)
	v_mfma_f32_32x32x16_bf16 v[66:81], v[126:129], v[118:121], v[66:81]
	ds_read_b64_tr_b16 v[4:5], v246 offset:56320
	ds_read_b64_tr_b16 v[6:7], v246 offset:56832
	v_max3_f32 v122, v122, v88, v89
	v_max3_f32 v123, v123, v106, v107
	s_nop 0
	s_waitcnt lgkmcnt(6)
	v_mfma_f32_32x32x16_bf16 v[18:33], v[130:133], v[114:117], v[18:33]
	v_max3_f32 v118, v122, v108, v109
	v_max3_f32 v119, v123, v90, v91
	s_nop 0
	s_waitcnt lgkmcnt(4)
	v_mfma_f32_32x32x16_bf16 v[34:49], v[130:133], v[8:11], v[34:49]
	v_max3_f32 v114, v118, v92, v93
	v_max3_f32 v115, v119, v110, v111
	s_nop 0
	s_waitcnt lgkmcnt(2)
	v_mfma_f32_32x32x16_bf16 v[50:65], v[130:133], v[12:15], v[50:65]
	v_max3_f32 v8, v114, v112, v113
	v_max3_f32 v9, v115, v94, v95
	s_nop 0
	s_waitcnt lgkmcnt(0)
	v_mfma_f32_32x32x16_bf16 v[66:81], v[130:133], v[4:7], v[66:81]
	v_max3_f32 v8, v8, v96, v97
	s_nop 0
	v_max_f32_e32 v8, v8, v9
	s_nop 0
	s_nop 0
	v_mov_b32_e32 v4, v8
	s_nop 1
	v_permlane32_swap_b32_e32 v8, v4
	v_max_f32_e32 v178, v8, v4
	v_add_f32_e32 v4, v17, v190
	v_add_f32_e32 v4, v191, v4
	v_add_f32_e32 v4, v192, v4
	v_add_f32_e32 v4, v193, v4
	v_add_f32_e32 v4, v194, v4
	v_add_f32_e32 v4, v195, v4
	v_add_f32_e32 v4, v196, v4
	v_add_f32_e32 v4, v197, v4
	v_add_f32_e32 v4, v198, v4
	v_add_f32_e32 v4, v199, v4
	v_add_f32_e32 v4, v200, v4
	v_add_f32_e32 v4, v201, v4
	v_add_f32_e32 v4, v202, v4
	v_add_f32_e32 v4, v179, v4
	v_add_f32_e32 v4, v180, v4
	v_add_f32_e32 v4, v181, v4
	v_add_f32_e32 v4, v203, v4
	v_add_f32_e32 v4, v182, v4
	v_add_f32_e32 v4, v183, v4
	v_add_f32_e32 v4, v184, v4
	v_add_f32_e32 v4, v185, v4
	v_add_f32_e32 v4, v186, v4
	v_add_f32_e32 v4, v187, v4
	v_add_f32_e32 v4, v134, v4
	v_add_f32_e32 v4, v135, v4
	v_add_f32_e32 v4, v136, v4
	v_add_f32_e32 v4, v137, v4
	v_add_f32_e32 v4, v138, v4
	v_add_f32_e32 v4, v139, v4
	v_add_f32_e32 v4, v140, v4
	s_waitcnt vmcnt(0) lgkmcnt(0)
	s_barrier
	v_add_f32_e32 v4, v141, v4
	v_add_f32_e32 v4, 0, v4
	s_add_i32 s87, s83, -4
	v_add_f32_e32 v251, v16, v4
	v_cmp_gt_u32_e64 s[6:7], 32, v243
	s_mov_b32 s88, 2
	v_lshl_add_u32 v16, v242, 2, s76
	s_movk_i32 s86, 0x2000
	s_mov_b32 s89, 0
	s_mov_b64 s[48:49], s[34:35]
	s_mov_b64 s[50:51], s[30:31]
	v_sub_f32_e32 v146, 0, v247
	v_sub_f32_e32 v147, 0, v247
	v_sub_f32_e32 v148, 0, v247
	v_sub_f32_e32 v149, 0, v247
	v_sub_f32_e32 v150, 0, v247
	v_sub_f32_e32 v151, 0, v247
	v_sub_f32_e32 v152, 0, v247
	v_sub_f32_e32 v153, 0, v247
	v_sub_f32_e32 v154, 0, v247
	v_sub_f32_e32 v155, 0, v247
	v_sub_f32_e32 v156, 0, v247
	v_sub_f32_e32 v157, 0, v247
	v_sub_f32_e32 v158, 0, v247
	v_sub_f32_e32 v159, 0, v247
	v_sub_f32_e32 v160, 0, v247
	v_sub_f32_e32 v161, 0, v247
	v_sub_f32_e32 v82, v82, v247
	v_sub_f32_e32 v83, v83, v247
	v_sub_f32_e32 v84, v84, v247
	v_sub_f32_e32 v85, v85, v247
	v_sub_f32_e32 v86, v86, v247
	v_sub_f32_e32 v87, v87, v247
	v_sub_f32_e32 v88, v88, v247
	v_sub_f32_e32 v89, v89, v247
	v_sub_f32_e32 v90, v90, v247
	v_sub_f32_e32 v91, v91, v247
	v_sub_f32_e32 v92, v92, v247
	v_sub_f32_e32 v93, v93, v247
	v_sub_f32_e32 v94, v94, v247
	v_sub_f32_e32 v95, v95, v247
	v_sub_f32_e32 v96, v96, v247
	v_sub_f32_e32 v97, v97, v247
	v_sub_f32_e32 v98, v98, v247
	v_sub_f32_e32 v99, v99, v247
	v_sub_f32_e32 v100, v100, v247
	v_sub_f32_e32 v101, v101, v247
	v_sub_f32_e32 v102, v102, v247
	v_sub_f32_e32 v103, v103, v247
	v_sub_f32_e32 v104, v104, v247
	v_sub_f32_e32 v105, v105, v247
	v_sub_f32_e32 v106, v106, v247
	v_sub_f32_e32 v107, v107, v247
	v_sub_f32_e32 v108, v108, v247
	v_sub_f32_e32 v109, v109, v247
	v_sub_f32_e32 v110, v110, v247
	v_sub_f32_e32 v111, v111, v247
	v_sub_f32_e32 v112, v112, v247
	v_sub_f32_e32 v113, v113, v247
	v_sub_f32_e32 v178, v178, v247
	s_branch .LBB0_436
.LBB0_434:
	s_or_b64 exec, exec, s[58:59]
	s_waitcnt lgkmcnt(0)
	v_add_u32_e32 v108, s76, v2
	ds_read_b128 v[96:99], v108 offset:64
	ds_read_b128 v[100:103], v108 offset:96
	ds_read_b128 v[104:107], v108
	ds_read_b128 v[108:111], v108 offset:32
	v_add_f32_e32 v247, v247, v94
	v_sub_f32_e32 v146, v146, v94
	v_sub_f32_e32 v147, v147, v94
	v_sub_f32_e32 v148, v148, v94
	v_sub_f32_e32 v149, v149, v94
	v_sub_f32_e32 v150, v150, v94
	v_sub_f32_e32 v151, v151, v94
	v_sub_f32_e32 v152, v152, v94
	v_sub_f32_e32 v153, v153, v94
	v_sub_f32_e32 v154, v154, v94
	v_sub_f32_e32 v155, v155, v94
	v_sub_f32_e32 v156, v156, v94
	v_sub_f32_e32 v157, v157, v94
	v_sub_f32_e32 v158, v158, v94
	v_sub_f32_e32 v159, v159, v94
	v_sub_f32_e32 v160, v160, v94
	v_sub_f32_e32 v161, v161, v94
	v_sub_f32_e32 v114, v114, v94
	v_sub_f32_e32 v115, v115, v94
	v_sub_f32_e32 v116, v116, v94
	v_sub_f32_e32 v117, v117, v94
	v_sub_f32_e32 v118, v118, v94
	v_sub_f32_e32 v119, v119, v94
	v_sub_f32_e32 v120, v120, v94
	v_sub_f32_e32 v121, v121, v94
	v_sub_f32_e32 v122, v122, v94
	v_sub_f32_e32 v123, v123, v94
	v_sub_f32_e32 v124, v124, v94
	v_sub_f32_e32 v125, v125, v94
	v_sub_f32_e32 v126, v126, v94
	v_sub_f32_e32 v127, v127, v94
	v_sub_f32_e32 v128, v128, v94
	v_sub_f32_e32 v129, v129, v94
	v_sub_f32_e32 v130, v130, v94
	v_sub_f32_e32 v131, v131, v94
	v_sub_f32_e32 v132, v132, v94
	v_sub_f32_e32 v133, v133, v94
	v_sub_f32_e32 v134, v134, v94
	v_sub_f32_e32 v135, v135, v94
	v_sub_f32_e32 v136, v136, v94
	v_sub_f32_e32 v137, v137, v94
	v_sub_f32_e32 v138, v138, v94
	v_sub_f32_e32 v139, v139, v94
	v_sub_f32_e32 v140, v140, v94
	v_sub_f32_e32 v141, v141, v94
	v_sub_f32_e32 v142, v142, v94
	v_sub_f32_e32 v143, v143, v94
	v_sub_f32_e32 v144, v144, v94
	v_sub_f32_e32 v145, v145, v94
	v_mul_f32_e32 v17, v17, v95
	s_waitcnt lgkmcnt(2)
; #define SB() __builtin_amdgcn_sched_barrier(0)
; #define MF32(a,b,c) __builtin_amdgcn_mfma_f32_32x32x16_bf16(a,b,c,0,0,0)
; #define EXP1(x) x=__builtin_amdgcn_exp2f((x)-mh_)
; __device__ __forceinline__ bf16x8 vfrag(lds_cptr vp,int i){ const s16x4 lo=vtr(vp+(i&3)*4096+(i>>2)*1024), hh=vtr(vp+(i&3)*4096+(i>>2)*1024+512); return (bf16x8){lo[0],lo[1],lo[2],lo[3],hh[0],hh[1],hh[2],hh[3]}; }
; __device__ __forceinline__ u32x4 packw(const f32x16&p,int base){ u32x4 w; w[0]=cvtpk_s(p[base],p[base+1]); w[1]=cvtpk_s(p[base+2],p[base+3]); w[2]=cvtpk_s(p[base+4],p[base+5]); w[3]=cvtpk_s(p[base+6],p[base+7]); return w; }
; template<int THRL,bool FIRST> __device__ __forceinline__ void step_main(f32x16&p0,f32x16&p1,f32x16&n0,f32x16&n1,St&S,lds_cptr kpn,lds_cptr qp,lds_cptr vp,float*wsf,int r32,int hi,float&rm){
;     ...
;   bf16x8 ka=KF(0),kb=KF(1),kc=KF(2),kd=KF(3),qa=QF(0),qb=QF(1);
;   decide<THRL,FIRST>(rm,S,wsf,r32,hi);
;   u32x4 pw0,pw1,pw2,pw3; const float mh_=S.mhat; const f32x16 z=f32x16{};
;   SB();
;   n0=MF32(ka,qa,z); ka=KF(4); EXP1(p0[0]);EXP1(p0[1]);EXP1(p0[2]); SB();
;   n1=MF32(kb,qa,z); kb=KF(5); qa=QF(2); EXP1(p0[3]);EXP1(p0[4]);EXP1(p0[5]); SB();
;   n0=MF32(kc,qb,n0);   kc=KF(6); EXP1(p0[6]);EXP1(p0[7]);EXP1(p0[8]); SB();
;   n1=MF32(kd,qb,n1);   kd=KF(7); qb=QF(3); EXP1(p0[9]);EXP1(p0[10]);EXP1(p0[11]); SB();
;   bf16x8 vfa=vfrag(vp,0);
;   n0=MF32(ka,qa,n0);   EXP1(p0[12]);EXP1(p0[13]);EXP1(p0[14]); pw0=packw(p0,0); SB();
;   bf16x8 vfb=vfrag(vp,1);
;   n1=MF32(kb,qa,n1);   EXP1(p0[15]);EXP1(p1[0]);EXP1(p1[1]); SB();
;   bf16x8 vfc=vfrag(vp,2);
;   n0=MF32(kc,qb,n0);   EXP1(p1[2]);EXP1(p1[3]);EXP1(p1[4]); pw1=packw(p0,8); SB();
;   bf16x8 vfd=vfrag(vp,3);
;   n1=MF32(kd,qb,n1);   EXP1(p1[5]);EXP1(p1[6]);EXP1(p1[7]); SB();
;     ...
;   float sa=p0[0]+p0[1];
;     ...
;   PVG(0,pw0,vfa,4, p0[2],p0[3],p0[4],p0[5],   do{EXP1(p1[8]);EXP1(p1[9]);}while(0));
;   PVG(1,pw0,vfb,5, p0[6],p0[7],p0[8],p0[9], do{EXP1(p1[10]);EXP1(p1[11]);}while(0));
;   PVG(2,pw0,vfc,6, p0[10],p0[11],p0[12],p0[13], do{EXP1(p1[12]);EXP1(p1[13]);}while(0));
;   PVG(3,pw0,vfd,7, p0[14],p0[15],p1[0],p1[1],   do{EXP1(p1[14]);EXP1(p1[15]);}while(0));
;   PVG(4,pw1,vfa,8, p1[2],p1[3],p1[4],p1[5],   pw2=packw(p1,0));
;   PVG(5,pw1,vfb,9, p1[6],p1[7],p1[8],p1[9], pw3=packw(p1,8));
;   PVG(6,pw1,vfc,10, p1[10],p1[11],p1[12],p1[13], do{}while(0));
;   PVG(7,pw1,vfd,11, p1[14],p1[15],0.f,0.f, do{}while(0));
	v_pk_mul_f32 v[30:31], v[30:31], v[100:101]
	v_pk_mul_f32 v[26:27], v[26:27], v[96:97]
	s_waitcnt lgkmcnt(0)
	v_pk_mul_f32 v[22:23], v[22:23], v[108:109]
	v_pk_mul_f32 v[32:33], v[32:33], v[102:103]
	v_pk_mul_f32 v[28:29], v[28:29], v[98:99]
	v_pk_mul_f32 v[24:25], v[24:25], v[110:111]
	v_pk_mul_f32 v[20:21], v[20:21], v[106:107]
	v_pk_mul_f32 v[18:19], v[18:19], v[104:105]
	v_pk_mul_f32 v[46:47], v[46:47], v[100:101]
	v_pk_mul_f32 v[42:43], v[42:43], v[96:97]
	v_pk_mul_f32 v[38:39], v[38:39], v[108:109]
	v_pk_mul_f32 v[48:49], v[48:49], v[102:103]
	v_pk_mul_f32 v[44:45], v[44:45], v[98:99]
	v_pk_mul_f32 v[40:41], v[40:41], v[110:111]
	v_pk_mul_f32 v[36:37], v[36:37], v[106:107]
	v_pk_mul_f32 v[34:35], v[34:35], v[104:105]
	v_pk_mul_f32 v[62:63], v[62:63], v[100:101]
	v_pk_mul_f32 v[58:59], v[58:59], v[96:97]
	v_pk_mul_f32 v[54:55], v[54:55], v[108:109]
	v_pk_mul_f32 v[64:65], v[64:65], v[102:103]
	v_pk_mul_f32 v[60:61], v[60:61], v[98:99]
	v_pk_mul_f32 v[56:57], v[56:57], v[110:111]
	v_pk_mul_f32 v[52:53], v[52:53], v[106:107]
	v_pk_mul_f32 v[50:51], v[50:51], v[104:105]
	v_pk_mul_f32 v[78:79], v[78:79], v[100:101]
	v_pk_mul_f32 v[74:75], v[74:75], v[96:97]
	v_pk_mul_f32 v[70:71], v[70:71], v[108:109]
	v_pk_mul_f32 v[80:81], v[80:81], v[102:103]
	v_pk_mul_f32 v[76:77], v[76:77], v[98:99]
	v_pk_mul_f32 v[72:73], v[72:73], v[110:111]
	v_pk_mul_f32 v[68:69], v[68:69], v[106:107]
	v_pk_mul_f32 v[66:67], v[66:67], v[104:105]
.LBB0_435:
	s_add_i32 s88, s88, 2
	s_waitcnt lgkmcnt(1)
	v_mfma_f32_32x32x16_bf16 v[98:113], v[90:93], v[86:89], v[146:161]
	v_exp_f32_e32 v130, v130
	v_exp_f32_e32 v131, v131
	ds_read_b128 v[180:183], v178 offset:4096
	v_exp_f32_e32 v132, v132
	v_exp_f32_e32 v133, v133
	v_exp_f32_e32 v134, v134
	v_exp_f32_e32 v135, v135
	v_mfma_f32_32x32x16_bf16 v[82:97], v[82:85], v[86:89], v[146:161]
	ds_read_b128 v[184:187], v178 offset:4608
	ds_read_b128 v[188:191], v248 offset:2048
	s_waitcnt lgkmcnt(3)
	v_mfma_f32_32x32x16_bf16 v[98:113], v[12:15], v[8:11], v[98:113]
	ds_read_b128 v[192:195], v178 offset:6144
	v_exp_f32_e32 v136, v136
	v_exp_f32_e32 v137, v137
	v_exp_f32_e32 v138, v138
	v_mfma_f32_32x32x16_bf16 v[82:97], v[4:7], v[8:11], v[82:97]
	ds_read_b128 v[12:15], v178 offset:6656
	ds_read_b128 v[196:199], v248 offset:3072
	v_exp_f32_e32 v139, v139
	v_exp_f32_e32 v140, v140
	v_exp_f32_e32 v141, v141
	s_waitcnt lgkmcnt(3)
	v_mfma_f32_32x32x16_bf16 v[98:113], v[180:183], v[188:191], v[98:113]
	v_exp_f32_e32 v142, v142
	ds_read_b64_tr_b16 v[4:5], v246 offset:40960
	ds_read_b64_tr_b16 v[6:7], v246 offset:41472
	v_exp_f32_e32 v143, v143
	v_exp_f32_e32 v144, v144
	v_cvt_pk_bf16_f32 v8, v130, v131
	v_cvt_pk_bf16_f32 v9, v132, v133
	v_cvt_pk_bf16_f32 v10, v134, v135
	v_cvt_pk_bf16_f32 v11, v136, v137
	v_mfma_f32_32x32x16_bf16 v[82:97], v[184:187], v[188:191], v[82:97]
	ds_read_b64_tr_b16 v[178:179], v246 offset:45056
	ds_read_b64_tr_b16 v[180:181], v246 offset:45568
	v_exp_f32_e32 v145, v145
	v_exp_f32_e32 v114, v114
	v_exp_f32_e32 v115, v115
	s_waitcnt lgkmcnt(4)
	v_mfma_f32_32x32x16_bf16 v[98:113], v[192:195], v[196:199], v[98:113]
	ds_read_b64_tr_b16 v[182:183], v246 offset:49152
	ds_read_b64_tr_b16 v[184:185], v246 offset:49664
	v_exp_f32_e32 v116, v116
	v_exp_f32_e32 v117, v117
	v_exp_f32_e32 v118, v118
	v_cvt_pk_bf16_f32 v186, v138, v139
	v_cvt_pk_bf16_f32 v187, v140, v141
	v_cvt_pk_bf16_f32 v188, v142, v143
	v_cvt_pk_bf16_f32 v189, v144, v145
	v_mfma_f32_32x32x16_bf16 v[82:97], v[12:15], v[196:199], v[82:97]
	ds_read_b64_tr_b16 v[190:191], v246 offset:53248
	ds_read_b64_tr_b16 v[192:193], v246 offset:53760
	v_exp_f32_e32 v119, v119
	v_exp_f32_e32 v120, v120
	v_exp_f32_e32 v121, v121
	s_waitcnt lgkmcnt(6)
	v_mfma_f32_32x32x16_bf16 v[18:33], v[8:11], v[4:7], v[18:33]
	ds_read_b64_tr_b16 v[12:13], v246 offset:41984
	ds_read_b64_tr_b16 v[14:15], v246 offset:42496
	v_add_f32_e32 v194, v130, v131
	v_exp_f32_e32 v122, v122
	v_exp_f32_e32 v123, v123
	v_add_f32_e32 v194, v132, v194
	v_add_f32_e32 v4, v133, v194
	v_add_f32_e32 v4, v134, v4
	v_add_f32_e32 v194, v135, v4
	s_waitcnt lgkmcnt(6)
	v_mfma_f32_32x32x16_bf16 v[34:49], v[8:11], v[178:181], v[34:49]
	ds_read_b64_tr_b16 v[4:5], v246 offset:46080
	ds_read_b64_tr_b16 v[6:7], v246 offset:46592
	v_exp_f32_e32 v124, v124
	v_exp_f32_e32 v125, v125
	v_add_f32_e32 v194, v136, v194
	v_add_f32_e32 v178, v137, v194
	v_add_f32_e32 v178, v138, v178
	v_add_f32_e32 v194, v139, v178
	s_waitcnt lgkmcnt(6)
	v_mfma_f32_32x32x16_bf16 v[50:65], v[8:11], v[182:185], v[50:65]
	ds_read_b64_tr_b16 v[178:179], v246 offset:50176
	ds_read_b64_tr_b16 v[180:181], v246 offset:50688
	v_exp_f32_e32 v126, v126
	v_exp_f32_e32 v127, v127
	v_add_f32_e32 v194, v140, v194
	v_add_f32_e32 v182, v141, v194
	v_add_f32_e32 v182, v142, v182
	v_add_f32_e32 v194, v143, v182
	s_waitcnt lgkmcnt(6)
	v_mfma_f32_32x32x16_bf16 v[66:81], v[8:11], v[190:193], v[66:81]
	ds_read_b64_tr_b16 v[182:183], v246 offset:54272
	ds_read_b64_tr_b16 v[184:185], v246 offset:54784
	v_exp_f32_e32 v128, v128
	v_exp_f32_e32 v129, v129
	v_add_f32_e32 v194, v144, v194
	v_add_f32_e32 v8, v145, v194
	v_add_f32_e32 v8, v114, v8
	v_add_f32_e32 v190, v115, v8
	s_waitcnt lgkmcnt(6)
	v_mfma_f32_32x32x16_bf16 v[18:33], v[186:189], v[12:15], v[18:33]
	ds_read_b64_tr_b16 v[8:9], v246 offset:43008
	ds_read_b64_tr_b16 v[10:11], v246 offset:43520
	v_add_f32_e32 v190, v116, v190
	v_add_f32_e32 v190, v117, v190
	v_add_f32_e32 v190, v118, v190
	v_add_f32_e32 v194, v119, v190
	v_cvt_pk_bf16_f32 v12, v114, v115
	v_cvt_pk_bf16_f32 v13, v116, v117
	v_cvt_pk_bf16_f32 v14, v118, v119
	v_cvt_pk_bf16_f32 v15, v120, v121
	s_waitcnt lgkmcnt(6)
; __device__ __forceinline__ int crow(int r,int hi){return (r&3)+8*(r>>2)+4*hi;}
; __device__ __forceinline__ float max3f(float a,float b,float c){float r;asm("v_max3_f32 %0, %1, %2, %3":"=v"(r):"v"(a),"v"(b),"v"(c));return r;}
; __device__ __forceinline__ float max2f(float a,float b){float r;asm("v_max_f32_e32 %0, %1, %2":"=v"(r):"v"(a),"v"(b));return r;}
;   #define PVG(i,PW,VF,NEXTI,X0,X1,Y0,Y1,EXTRA) do{ S.o[(i)&3]=MF32(__builtin_bit_cast(bf16x8,PW),VF,S.o[(i)&3]); if((NEXTI)<16){ VF=vfrag(vp,(NEXTI)<16?(NEXTI):0); } sa+=X0; sa+=X1; sa+=Y0; sa+=Y1; EXTRA; SB(); }while(0)
; template<int THRL,bool FIRST> __device__ __forceinline__ void decide(float rm,St&S,float*wsf,int r32,int hi){
;   if(FIRST){ S.mhat=rm; }
;   else if(__any(rm-S.mhat>(float)THRL)){
;     const float dl=__builtin_fmaxf(rm-S.mhat,0.f); S.mhat+=dl;
;     const float f=__builtin_amdgcn_exp2f(-dl); S.l_reg*=f; if(hi==0)wsf[r32]=f;
;     asm volatile("s_waitcnt lgkmcnt(0)":::"memory");
;     #pragma unroll
;     for(int r=0;r<16;++r){ const float fr=wsf[crow(r,hi)];
;       #pragma unroll
;       for(int d=0;d<4;++d)S.o[d][r]*=fr; }
; template<int THRL,bool FIRST> __device__ __forceinline__ void step_main(f32x16&p0,f32x16&p1,f32x16&n0,f32x16&n1,St&S,lds_cptr kpn,lds_cptr qp,lds_cptr vp,float*wsf,int r32,int hi,float&rm){
;     ...
;   PVG(8,pw2,vfa,12,0.f,0.f,0.f,0.f, do{ma=max3f(n0[0],n0[1],n1[0]);mb=max3f(n0[2],n0[3],n1[1]);PINAB();}while(0));
;   PVG(9,pw2,vfb,13,0.f,0.f,0.f,0.f, do{ma=max3f(ma,n1[2],n1[3]);mb=max3f(mb,n0[4],n0[5]);PINAB();}while(0));
;   PVG(10,pw2,vfc,14,0.f,0.f,0.f,0.f, do{ma=max3f(ma,n0[6],n0[7]);mb=max3f(mb,n1[4],n1[5]);PINAB();}while(0));
;   PVG(11,pw2,vfd,15,0.f,0.f,0.f,0.f, do{ma=max3f(ma,n1[6],n1[7]);mb=max3f(mb,n0[8],n0[9]);PINAB();}while(0));
;   PVG(12,pw3,vfa,16,0.f,0.f,0.f,0.f, do{ma=max3f(ma,n0[10],n0[11]);mb=max3f(mb,n1[8],n1[9]);PINAB();}while(0));
;   PVG(13,pw3,vfb,16,0.f,0.f,0.f,0.f, do{ma=max3f(ma,n1[10],n1[11]);mb=max3f(mb,n0[12],n0[13]);PINAB();}while(0));
;   PVG(14,pw3,vfc,16,0.f,0.f,0.f,0.f, do{ma=max3f(ma,n0[14],n0[15]);mb=max3f(mb,n1[12],n1[13]);PINAB();}while(0));
;   PVG(15,pw3,vfd,16,0.f,0.f,0.f,0.f, do{ma=max3f(ma,n1[14],n1[15]);ma=max2f(ma,mb);PINAB();}while(0));
;     ...
;   { auto rr=__builtin_amdgcn_permlane32_swap(__float_as_uint(ma),__float_as_uint(ma),false,false); rm=max2f(__uint_as_float(rr[0]),__uint_as_float(rr[1])); }
;     ...
;   S.l_reg+=sa;
; }
	v_mfma_f32_32x32x16_bf16 v[34:49], v[186:189], v[4:7], v[34:49]
	ds_read_b64_tr_b16 v[190:191], v246 offset:47104
	ds_read_b64_tr_b16 v[192:193], v246 offset:47616
	v_add_f32_e32 v194, v120, v194
	v_add_f32_e32 v194, v121, v194
	v_add_f32_e32 v194, v122, v194
	v_add_f32_e32 v198, v123, v194
	v_cvt_pk_bf16_f32 v4, v122, v123
	v_cvt_pk_bf16_f32 v5, v124, v125
	v_cvt_pk_bf16_f32 v6, v126, v127
	v_cvt_pk_bf16_f32 v7, v128, v129
	s_waitcnt lgkmcnt(6)
	v_mfma_f32_32x32x16_bf16 v[50:65], v[186:189], v[178:181], v[50:65]
	ds_read_b64_tr_b16 v[194:195], v246 offset:51200
	ds_read_b64_tr_b16 v[196:197], v246 offset:51712
	v_add_f32_e32 v198, v124, v198
	v_add_f32_e32 v198, v125, v198
	v_add_f32_e32 v198, v126, v198
	v_add_f32_e32 v198, v127, v198
	s_waitcnt lgkmcnt(6)
	v_mfma_f32_32x32x16_bf16 v[66:81], v[186:189], v[182:185], v[66:81]
	ds_read_b64_tr_b16 v[178:179], v246 offset:55296
	ds_read_b64_tr_b16 v[180:181], v246 offset:55808
	v_add_f32_e32 v198, v128, v198
	v_add_f32_e32 v198, v129, v198
	v_add_f32_e32 v198, 0, v198
	s_waitcnt lgkmcnt(6)
	v_mfma_f32_32x32x16_bf16 v[18:33], v[12:15], v[8:11], v[18:33]
	ds_read_b64_tr_b16 v[182:183], v246 offset:44032
	ds_read_b64_tr_b16 v[184:185], v246 offset:44544
	v_max3_f32 v186, v98, v99, v82
	v_max3_f32 v187, v100, v101, v83
	s_nop 0
	s_waitcnt lgkmcnt(6)
	v_mfma_f32_32x32x16_bf16 v[34:49], v[12:15], v[190:193], v[34:49]
	ds_read_b64_tr_b16 v[8:9], v246 offset:48128
	ds_read_b64_tr_b16 v[10:11], v246 offset:48640
	v_max3_f32 v199, v186, v84, v85
	v_max3_f32 v200, v187, v102, v103
	s_nop 0
	s_waitcnt lgkmcnt(6)
	v_mfma_f32_32x32x16_bf16 v[50:65], v[12:15], v[194:197], v[50:65]
	ds_read_b64_tr_b16 v[186:187], v246 offset:52224
	ds_read_b64_tr_b16 v[188:189], v246 offset:52736
	v_max3_f32 v199, v199, v104, v105
	v_max3_f32 v200, v200, v86, v87
	s_nop 0
	s_waitcnt lgkmcnt(6)
	v_mfma_f32_32x32x16_bf16 v[66:81], v[12:15], v[178:181], v[66:81]
	ds_read_b64_tr_b16 v[190:191], v246 offset:56320
	ds_read_b64_tr_b16 v[192:193], v246 offset:56832
	v_max3_f32 v194, v199, v88, v89
	v_max3_f32 v195, v200, v106, v107
	s_nop 0
	s_waitcnt lgkmcnt(6)
	v_mfma_f32_32x32x16_bf16 v[18:33], v[4:7], v[182:185], v[18:33]
	v_max3_f32 v12, v194, v108, v109
	v_max3_f32 v13, v195, v90, v91
	s_nop 0
	s_waitcnt lgkmcnt(4)
	v_mfma_f32_32x32x16_bf16 v[34:49], v[4:7], v[8:11], v[34:49]
	v_max3_f32 v12, v12, v92, v93
	v_max3_f32 v13, v13, v110, v111
	s_nop 0
	s_waitcnt lgkmcnt(2)
	v_mfma_f32_32x32x16_bf16 v[50:65], v[4:7], v[186:189], v[50:65]
	v_max3_f32 v8, v12, v112, v113
	v_max3_f32 v9, v13, v94, v95
	s_nop 0
	s_waitcnt lgkmcnt(0)
	v_mfma_f32_32x32x16_bf16 v[66:81], v[4:7], v[190:193], v[66:81]
	v_max3_f32 v8, v8, v96, v97
	s_nop 0
	v_max_f32_e32 v8, v8, v9
	s_nop 0
	s_add_i32 s4, s89, 0x2000
	s_cmpk_lg_i32 s89, 0x4000
	s_cselect_b32 s86, s4, 0
	s_add_u32 s50, s50, 0x180000
	s_addc_u32 s51, s51, 0
	s_add_u32 s48, s48, 0x180000
	s_waitcnt vmcnt(0) lgkmcnt(0)
	s_barrier
	s_addc_u32 s49, s49, 0
	v_mov_b32_e32 v4, v8
	v_add_f32_e32 v251, v17, v198
	s_cmp_lt_u32 s88, s87
	v_permlane32_swap_b32_e32 v8, v4
	v_max_f32_e32 v178, v8, v4
	s_cbranch_scc0 .LBB0_443
.LBB0_436:
	s_add_u32 s58, s50, 0xfff40000
	s_addc_u32 s59, s51, -1
	s_add_i32 s4, s86, s80
	s_mov_b32 s5, m0
	s_mov_b32 m0, s4
	s_nop 0
	global_load_lds_dwordx4 v252, s[58:59]
	s_mov_b32 m0, s5
	s_mov_b32 s4, m0
	s_mov_b32 m0, s77
	s_nop 0
	global_load_lds_dwordx4 v250, s[48:49]
	s_mov_b32 m0, s4
	s_add_u32 s58, s48, 0x80
	s_addc_u32 s59, s49, 0
	s_mov_b32 s4, m0
	s_mov_b32 m0, s39
	s_nop 0
	global_load_lds_dwordx4 v250, s[58:59]
	s_mov_b32 m0, s4
	v_add_u32_e32 v17, s89, v249
	ds_read_b128 v[122:125], v17
	ds_read_b128 v[114:117], v17 offset:512
	ds_read_b128 v[12:15], v17 offset:2048
	ds_read_b128 v[4:7], v17 offset:2560
	ds_read_b128 v[118:121], v248
	ds_read_b128 v[8:11], v248 offset:1024
	v_mov_b32_e32 v126, v178
	v_cmp_lt_f32_e32 vcc, s67, v126
	s_cbranch_vccz .LBB0_440
	v_max_f32_e32 v126, v126, v126
	v_max_f32_e32 v126, 0, v126
	v_exp_f32_e64 v127, -v126
	s_and_saveexec_b64 s[58:59], s[6:7]
	ds_write_b32 v16, v127
	s_or_b64 exec, exec, s[58:59]
	s_waitcnt lgkmcnt(0)
	v_add_u32_e32 v140, s76, v2
	ds_read_b128 v[128:131], v140 offset:64
	ds_read_b128 v[132:135], v140 offset:96
	ds_read_b128 v[136:139], v140
	ds_read_b128 v[140:143], v140 offset:32
	v_add_f32_e32 v247, v247, v126
	v_sub_f32_e32 v146, v146, v126
	v_sub_f32_e32 v147, v147, v126
	v_sub_f32_e32 v148, v148, v126
	v_sub_f32_e32 v149, v149, v126
	v_sub_f32_e32 v150, v150, v126
	v_sub_f32_e32 v151, v151, v126
	v_sub_f32_e32 v152, v152, v126
	v_sub_f32_e32 v153, v153, v126
	v_sub_f32_e32 v154, v154, v126
	v_sub_f32_e32 v155, v155, v126
	v_sub_f32_e32 v156, v156, v126
	v_sub_f32_e32 v157, v157, v126
	v_sub_f32_e32 v158, v158, v126
	v_sub_f32_e32 v159, v159, v126
	v_sub_f32_e32 v160, v160, v126
	v_sub_f32_e32 v161, v161, v126
	v_sub_f32_e32 v82, v82, v126
	v_sub_f32_e32 v83, v83, v126
	v_sub_f32_e32 v84, v84, v126
	v_sub_f32_e32 v85, v85, v126
	v_sub_f32_e32 v86, v86, v126
	v_sub_f32_e32 v87, v87, v126
	v_sub_f32_e32 v88, v88, v126
	v_sub_f32_e32 v89, v89, v126
	v_sub_f32_e32 v90, v90, v126
	v_sub_f32_e32 v91, v91, v126
	v_sub_f32_e32 v92, v92, v126
	v_sub_f32_e32 v93, v93, v126
	v_sub_f32_e32 v94, v94, v126
	v_sub_f32_e32 v95, v95, v126
	v_sub_f32_e32 v96, v96, v126
	v_sub_f32_e32 v97, v97, v126
	v_sub_f32_e32 v98, v98, v126
	v_sub_f32_e32 v99, v99, v126
	v_sub_f32_e32 v100, v100, v126
	v_sub_f32_e32 v101, v101, v126
	v_sub_f32_e32 v102, v102, v126
	v_sub_f32_e32 v103, v103, v126
	v_sub_f32_e32 v104, v104, v126
	v_sub_f32_e32 v105, v105, v126
	v_sub_f32_e32 v106, v106, v126
	v_sub_f32_e32 v107, v107, v126
	v_sub_f32_e32 v108, v108, v126
	v_sub_f32_e32 v109, v109, v126
	v_sub_f32_e32 v110, v110, v126
	v_sub_f32_e32 v111, v111, v126
	v_sub_f32_e32 v112, v112, v126
	v_sub_f32_e32 v113, v113, v126
	v_mul_f32_e32 v251, v251, v127
	s_waitcnt lgkmcnt(2)
; __device__ __forceinline__ int crow(int r,int hi){return (r&3)+8*(r>>2)+4*hi;}
; #define SB() __builtin_amdgcn_sched_barrier(0)
; #define MF32(a,b,c) __builtin_amdgcn_mfma_f32_32x32x16_bf16(a,b,c,0,0,0)
; #define EXP1(x) x=__builtin_amdgcn_exp2f((x)-mh_)
; __device__ __forceinline__ bf16x8 vfrag(lds_cptr vp,int i){ const s16x4 lo=vtr(vp+(i&3)*4096+(i>>2)*1024), hh=vtr(vp+(i&3)*4096+(i>>2)*1024+512); return (bf16x8){lo[0],lo[1],lo[2],lo[3],hh[0],hh[1],hh[2],hh[3]}; }
;   #define KF(i) LDSQ(kpn+((i)>>1)*2048+((i)&1)*512)
;   #define QF(d0) LDSQ(qp+(d0)*1024)
; template<int THRL,bool FIRST> __device__ __forceinline__ void decide(float rm,St&S,float*wsf,int r32,int hi){
;     ...
;     for(int r=0;r<16;++r){ const float fr=wsf[crow(r,hi)];
;       #pragma unroll
;       for(int d=0;d<4;++d)S.o[d][r]*=fr; }
; template<int THRL,bool FIRST> __device__ __forceinline__ void step_main(f32x16&p0,f32x16&p1,f32x16&n0,f32x16&n1,St&S,lds_cptr kpn,lds_cptr qp,lds_cptr vp,float*wsf,int r32,int hi,float&rm){
;     ...
;   bf16x8 ka=KF(0),kb=KF(1),kc=KF(2),kd=KF(3),qa=QF(0),qb=QF(1);
;   decide<THRL,FIRST>(rm,S,wsf,r32,hi);
;   u32x4 pw0,pw1,pw2,pw3; const float mh_=S.mhat; const f32x16 z=f32x16{};
;   SB();
;   n0=MF32(ka,qa,z); ka=KF(4); EXP1(p0[0]);EXP1(p0[1]);EXP1(p0[2]); SB();
;   n1=MF32(kb,qa,z); kb=KF(5); qa=QF(2); EXP1(p0[3]);EXP1(p0[4]);EXP1(p0[5]); SB();
;   n0=MF32(kc,qb,n0);   kc=KF(6); EXP1(p0[6]);EXP1(p0[7]);EXP1(p0[8]); SB();
;   n1=MF32(kd,qb,n1);   kd=KF(7); qb=QF(3); EXP1(p0[9]);EXP1(p0[10]);EXP1(p0[11]); SB();
;   bf16x8 vfa=vfrag(vp,0);
;   n0=MF32(ka,qa,n0);   EXP1(p0[12]);EXP1(p0[13]);EXP1(p0[14]); pw0=packw(p0,0); SB();
;   bf16x8 vfb=vfrag(vp,1);
;   n1=MF32(kb,qa,n1);   EXP1(p0[15]);EXP1(p1[0]);EXP1(p1[1]); SB();
;   bf16x8 vfc=vfrag(vp,2);
;   n0=MF32(kc,qb,n0);   EXP1(p1[2]);EXP1(p1[3]);EXP1(p1[4]); pw1=packw(p0,8); SB();
;   bf16x8 vfd=vfrag(vp,3);
;   n1=MF32(kd,qb,n1);   EXP1(p1[5]);EXP1(p1[6]);EXP1(p1[7]); SB();
;     ...
;   float sa=p0[0]+p0[1];
;     ...
;   PVG(0,pw0,vfa,4, p0[2],p0[3],p0[4],p0[5],   do{EXP1(p1[8]);EXP1(p1[9]);}while(0));
;   PVG(1,pw0,vfb,5, p0[6],p0[7],p0[8],p0[9], do{EXP1(p1[10]);EXP1(p1[11]);}while(0));
;   PVG(2,pw0,vfc,6, p0[10],p0[11],p0[12],p0[13], do{EXP1(p1[12]);EXP1(p1[13]);}while(0));
;   PVG(3,pw0,vfd,7, p0[14],p0[15],p1[0],p1[1],   do{EXP1(p1[14]);EXP1(p1[15]);}while(0));
	v_pk_mul_f32 v[30:31], v[30:31], v[132:133]
	v_pk_mul_f32 v[26:27], v[26:27], v[128:129]
	s_waitcnt lgkmcnt(0)
	v_pk_mul_f32 v[22:23], v[22:23], v[140:141]
	v_pk_mul_f32 v[32:33], v[32:33], v[134:135]
	v_pk_mul_f32 v[28:29], v[28:29], v[130:131]
	v_pk_mul_f32 v[24:25], v[24:25], v[142:143]
	v_pk_mul_f32 v[20:21], v[20:21], v[138:139]
	v_pk_mul_f32 v[18:19], v[18:19], v[136:137]
	v_pk_mul_f32 v[46:47], v[46:47], v[132:133]
	v_pk_mul_f32 v[42:43], v[42:43], v[128:129]
	v_pk_mul_f32 v[38:39], v[38:39], v[140:141]
	v_pk_mul_f32 v[48:49], v[48:49], v[134:135]
	v_pk_mul_f32 v[44:45], v[44:45], v[130:131]
	v_pk_mul_f32 v[40:41], v[40:41], v[142:143]
	v_pk_mul_f32 v[36:37], v[36:37], v[138:139]
	v_pk_mul_f32 v[34:35], v[34:35], v[136:137]
	v_pk_mul_f32 v[62:63], v[62:63], v[132:133]
	v_pk_mul_f32 v[58:59], v[58:59], v[128:129]
	v_pk_mul_f32 v[54:55], v[54:55], v[140:141]
	v_pk_mul_f32 v[64:65], v[64:65], v[134:135]
	v_pk_mul_f32 v[60:61], v[60:61], v[130:131]
	v_pk_mul_f32 v[56:57], v[56:57], v[142:143]
	v_pk_mul_f32 v[52:53], v[52:53], v[138:139]
	v_pk_mul_f32 v[50:51], v[50:51], v[136:137]
	v_pk_mul_f32 v[78:79], v[78:79], v[132:133]
	v_pk_mul_f32 v[74:75], v[74:75], v[128:129]
	v_pk_mul_f32 v[70:71], v[70:71], v[140:141]
	v_pk_mul_f32 v[80:81], v[80:81], v[134:135]
	v_pk_mul_f32 v[76:77], v[76:77], v[130:131]
	v_pk_mul_f32 v[72:73], v[72:73], v[142:143]
	v_pk_mul_f32 v[68:69], v[68:69], v[138:139]
	v_pk_mul_f32 v[66:67], v[66:67], v[136:137]
.LBB0_440:
	s_waitcnt lgkmcnt(1)
	v_mfma_f32_32x32x16_bf16 v[130:145], v[122:125], v[118:121], v[146:161]
	ds_read_b128 v[178:181], v17 offset:4096
	v_exp_f32_e32 v190, v98
	v_exp_f32_e32 v191, v99
	v_exp_f32_e32 v192, v100
	v_mfma_f32_32x32x16_bf16 v[114:129], v[114:117], v[118:121], v[146:161]
	ds_read_b128 v[182:185], v17 offset:4608
	ds_read_b128 v[186:189], v248 offset:2048
	v_exp_f32_e32 v193, v101
	v_exp_f32_e32 v194, v102
	v_exp_f32_e32 v195, v103
	s_waitcnt lgkmcnt(3)
	v_mfma_f32_32x32x16_bf16 v[130:145], v[12:15], v[8:11], v[130:145]
	ds_read_b128 v[98:101], v17 offset:6144
	v_exp_f32_e32 v196, v104
	v_exp_f32_e32 v197, v105
	v_exp_f32_e32 v198, v106
	v_mfma_f32_32x32x16_bf16 v[114:129], v[4:7], v[8:11], v[114:129]
	ds_read_b128 v[12:15], v17 offset:6656
	ds_read_b128 v[102:105], v248 offset:3072
	v_exp_f32_e32 v17, v107
	v_exp_f32_e32 v199, v108
	v_exp_f32_e32 v200, v109
	s_waitcnt lgkmcnt(3)
	v_mfma_f32_32x32x16_bf16 v[130:145], v[178:181], v[186:189], v[130:145]
	v_exp_f32_e32 v201, v110
	ds_read_b64_tr_b16 v[4:5], v246 offset:24576
	ds_read_b64_tr_b16 v[6:7], v246 offset:25088
	v_exp_f32_e32 v202, v111
	v_exp_f32_e32 v178, v112
	v_cvt_pk_bf16_f32 v8, v190, v191
	v_cvt_pk_bf16_f32 v9, v192, v193
	v_cvt_pk_bf16_f32 v10, v194, v195
	v_cvt_pk_bf16_f32 v11, v196, v197
	v_mfma_f32_32x32x16_bf16 v[114:129], v[182:185], v[186:189], v[114:129]
	ds_read_b64_tr_b16 v[106:107], v246 offset:28672
	ds_read_b64_tr_b16 v[108:109], v246 offset:29184
	v_exp_f32_e32 v180, v82
	v_exp_f32_e32 v179, v113
	v_exp_f32_e32 v181, v83
	s_waitcnt lgkmcnt(4)
	v_mfma_f32_32x32x16_bf16 v[130:145], v[98:101], v[102:105], v[130:145]
	ds_read_b64_tr_b16 v[110:111], v246 offset:32768
	ds_read_b64_tr_b16 v[112:113], v246 offset:33280
	v_exp_f32_e32 v182, v84
	v_exp_f32_e32 v183, v85
	v_exp_f32_e32 v184, v86
	v_cvt_pk_bf16_f32 v82, v198, v17
	v_cvt_pk_bf16_f32 v83, v199, v200
	v_cvt_pk_bf16_f32 v84, v201, v202
	v_cvt_pk_bf16_f32 v85, v178, v179
	v_mfma_f32_32x32x16_bf16 v[114:129], v[12:15], v[102:105], v[114:129]
	ds_read_b64_tr_b16 v[98:99], v246 offset:36864
	ds_read_b64_tr_b16 v[100:101], v246 offset:37376
	v_exp_f32_e32 v185, v87
	v_exp_f32_e32 v186, v88
	v_exp_f32_e32 v187, v89
	s_waitcnt lgkmcnt(6)
	v_mfma_f32_32x32x16_bf16 v[18:33], v[8:11], v[4:7], v[18:33]
	v_add_f32_e32 v86, v190, v191
	ds_read_b64_tr_b16 v[12:13], v246 offset:25600
	ds_read_b64_tr_b16 v[14:15], v246 offset:26112
	v_add_f32_e32 v86, v192, v86
	v_exp_f32_e32 v103, v91
	v_add_f32_e32 v4, v193, v86
	v_add_f32_e32 v4, v194, v4
	v_add_f32_e32 v86, v195, v4
	v_exp_f32_e32 v102, v90
	s_waitcnt lgkmcnt(6)
	v_mfma_f32_32x32x16_bf16 v[34:49], v[8:11], v[106:109], v[34:49]
	ds_read_b64_tr_b16 v[4:5], v246 offset:29696
	ds_read_b64_tr_b16 v[6:7], v246 offset:30208
	v_add_f32_e32 v86, v196, v86
	v_add_f32_e32 v86, v197, v86
	v_add_f32_e32 v86, v198, v86
	v_exp_f32_e32 v104, v92
	v_add_f32_e32 v17, v17, v86
	v_exp_f32_e32 v105, v93
	s_waitcnt lgkmcnt(6)
	v_mfma_f32_32x32x16_bf16 v[50:65], v[8:11], v[110:113], v[50:65]
	ds_read_b64_tr_b16 v[86:87], v246 offset:33792
	ds_read_b64_tr_b16 v[88:89], v246 offset:34304
	v_add_f32_e32 v17, v199, v17
	v_add_f32_e32 v17, v200, v17
	v_add_f32_e32 v17, v201, v17
	v_exp_f32_e32 v106, v94
	v_add_f32_e32 v17, v202, v17
	v_exp_f32_e32 v107, v95
	s_waitcnt lgkmcnt(6)
; #define EXP1(x) x=__builtin_amdgcn_exp2f((x)-mh_)
; template<int THRL,bool FIRST> __device__ __forceinline__ void step_main(f32x16&p0,f32x16&p1,f32x16&n0,f32x16&n1,St&S,lds_cptr kpn,lds_cptr qp,lds_cptr vp,float*wsf,int r32,int hi,float&rm){
;     ...
;   PVG(0,pw0,vfa,4, p0[2],p0[3],p0[4],p0[5],   do{EXP1(p1[8]);EXP1(p1[9]);}while(0));
;   PVG(1,pw0,vfb,5, p0[6],p0[7],p0[8],p0[9], do{EXP1(p1[10]);EXP1(p1[11]);}while(0));
;   PVG(2,pw0,vfc,6, p0[10],p0[11],p0[12],p0[13], do{EXP1(p1[12]);EXP1(p1[13]);}while(0));
;   PVG(3,pw0,vfd,7, p0[14],p0[15],p1[0],p1[1],   do{EXP1(p1[14]);EXP1(p1[15]);}while(0));
;   PVG(4,pw1,vfa,8, p1[2],p1[3],p1[4],p1[5],   pw2=packw(p1,0));
;   PVG(5,pw1,vfb,9, p1[6],p1[7],p1[8],p1[9], pw3=packw(p1,8));
;   PVG(6,pw1,vfc,10, p1[10],p1[11],p1[12],p1[13], do{}while(0));
;   PVG(7,pw1,vfd,11, p1[14],p1[15],0.f,0.f, do{}while(0));
;   float ma,mb;
;     ...
;   PVG(8,pw2,vfa,12,0.f,0.f,0.f,0.f, do{ma=max3f(n0[0],n0[1],n1[0]);mb=max3f(n0[2],n0[3],n1[1]);PINAB();}while(0));
;   PVG(9,pw2,vfb,13,0.f,0.f,0.f,0.f, do{ma=max3f(ma,n1[2],n1[3]);mb=max3f(mb,n0[4],n0[5]);PINAB();}while(0));
;   PVG(10,pw2,vfc,14,0.f,0.f,0.f,0.f, do{ma=max3f(ma,n0[6],n0[7]);mb=max3f(mb,n1[4],n1[5]);PINAB();}while(0));
;   PVG(11,pw2,vfd,15,0.f,0.f,0.f,0.f, do{ma=max3f(ma,n1[6],n1[7]);mb=max3f(mb,n0[8],n0[9]);PINAB();}while(0));
;   PVG(12,pw3,vfa,16,0.f,0.f,0.f,0.f, do{ma=max3f(ma,n0[10],n0[11]);mb=max3f(mb,n1[8],n1[9]);PINAB();}while(0));
;   PVG(13,pw3,vfb,16,0.f,0.f,0.f,0.f, do{ma=max3f(ma,n1[10],n1[11]);mb=max3f(mb,n0[12],n0[13]);PINAB();}while(0));
;   PVG(14,pw3,vfc,16,0.f,0.f,0.f,0.f, do{ma=max3f(ma,n0[14],n0[15]);mb=max3f(mb,n1[12],n1[13]);PINAB();}while(0));
;   PVG(15,pw3,vfd,16,0.f,0.f,0.f,0.f, do{ma=max3f(ma,n1[14],n1[15]);ma=max2f(ma,mb);PINAB();}while(0));
;     ...
;   { auto rr=__builtin_amdgcn_permlane32_swap(__float_as_uint(ma),__float_as_uint(ma),false,false); rm=max2f(__uint_as_float(rr[0]),__uint_as_float(rr[1])); }
;     ...
;   S.l_reg+=sa;
; }
; template<int THRL> __device__ __forceinline__ void unit(int qb,const bf16*Q,const bf16*K,const bf16*V,bf16*O,char*shm){
;     ...
;       DMA_K(t+2,ks2); DMA_V(t+1,VBUF);
;       step_main<THRL,false>(pA0,pA1,pB0,pB1,S,kp0+ks1,qp,vp0,wsf,r32,hi,rm); A128_WAITBAR(); ROT();
;       DMA_K(t+3,ks2); DMA_V(t+2,0);
;       step_main<THRL,false>(pB0,pB1,pA0,pA1,S,kp0+ks1,qp,vp0+VBUF,wsf,r32,hi,rm); A128_WAITBAR(); ROT();
	v_mfma_f32_32x32x16_bf16 v[66:81], v[8:11], v[98:101], v[66:81]
	ds_read_b64_tr_b16 v[90:91], v246 offset:37888
	ds_read_b64_tr_b16 v[92:93], v246 offset:38400
	v_add_f32_e32 v17, v178, v17
	v_add_f32_e32 v8, v179, v17
	v_add_f32_e32 v8, v180, v8
	v_exp_f32_e32 v108, v96
	v_add_f32_e32 v17, v181, v8
	v_exp_f32_e32 v109, v97
	s_waitcnt lgkmcnt(6)
	v_mfma_f32_32x32x16_bf16 v[18:33], v[82:85], v[12:15], v[18:33]
	ds_read_b64_tr_b16 v[8:9], v246 offset:26624
	ds_read_b64_tr_b16 v[10:11], v246 offset:27136
	v_add_f32_e32 v17, v182, v17
	v_add_f32_e32 v17, v183, v17
	v_add_f32_e32 v17, v184, v17
	v_add_f32_e32 v17, v185, v17
	v_cvt_pk_bf16_f32 v12, v180, v181
	v_cvt_pk_bf16_f32 v13, v182, v183
	v_cvt_pk_bf16_f32 v14, v184, v185
	v_cvt_pk_bf16_f32 v15, v186, v187
	s_waitcnt lgkmcnt(6)
	v_mfma_f32_32x32x16_bf16 v[34:49], v[82:85], v[4:7], v[34:49]
	ds_read_b64_tr_b16 v[94:95], v246 offset:30720
	ds_read_b64_tr_b16 v[96:97], v246 offset:31232
	v_add_f32_e32 v17, v186, v17
	v_add_f32_e32 v17, v187, v17
	v_add_f32_e32 v17, v102, v17
	v_add_f32_e32 v17, v103, v17
	v_cvt_pk_bf16_f32 v4, v102, v103
	v_cvt_pk_bf16_f32 v5, v104, v105
	v_cvt_pk_bf16_f32 v6, v106, v107
	v_cvt_pk_bf16_f32 v7, v108, v109
	s_waitcnt lgkmcnt(6)
	v_mfma_f32_32x32x16_bf16 v[50:65], v[82:85], v[86:89], v[50:65]
	ds_read_b64_tr_b16 v[98:99], v246 offset:34816
	ds_read_b64_tr_b16 v[100:101], v246 offset:35328
	v_add_f32_e32 v17, v104, v17
	v_add_f32_e32 v17, v105, v17
	v_add_f32_e32 v17, v106, v17
	v_add_f32_e32 v17, v107, v17
	s_waitcnt lgkmcnt(6)
	v_mfma_f32_32x32x16_bf16 v[66:81], v[82:85], v[90:93], v[66:81]
	ds_read_b64_tr_b16 v[86:87], v246 offset:38912
	ds_read_b64_tr_b16 v[88:89], v246 offset:39424
	v_add_f32_e32 v17, v108, v17
	v_add_f32_e32 v17, v109, v17
	v_add_f32_e32 v17, 0, v17
	s_waitcnt lgkmcnt(6)
	v_mfma_f32_32x32x16_bf16 v[18:33], v[12:15], v[8:11], v[18:33]
	ds_read_b64_tr_b16 v[82:83], v246 offset:27648
	ds_read_b64_tr_b16 v[84:85], v246 offset:28160
	v_max3_f32 v90, v130, v131, v114
	v_max3_f32 v91, v132, v133, v115
	s_nop 0
	s_waitcnt lgkmcnt(6)
	v_mfma_f32_32x32x16_bf16 v[34:49], v[12:15], v[94:97], v[34:49]
	ds_read_b64_tr_b16 v[8:9], v246 offset:31744
	ds_read_b64_tr_b16 v[10:11], v246 offset:32256
	v_max3_f32 v102, v90, v116, v117
	v_max3_f32 v103, v91, v134, v135
	s_nop 0
	s_waitcnt lgkmcnt(6)
	v_mfma_f32_32x32x16_bf16 v[50:65], v[12:15], v[98:101], v[50:65]
	ds_read_b64_tr_b16 v[90:91], v246 offset:35840
	ds_read_b64_tr_b16 v[92:93], v246 offset:36352
	v_max3_f32 v102, v102, v136, v137
	v_max3_f32 v103, v103, v118, v119
	s_nop 0
	s_waitcnt lgkmcnt(6)
	v_mfma_f32_32x32x16_bf16 v[66:81], v[12:15], v[86:89], v[66:81]
	ds_read_b64_tr_b16 v[94:95], v246 offset:39936
	ds_read_b64_tr_b16 v[96:97], v246 offset:40448
	v_max3_f32 v98, v102, v120, v121
	v_max3_f32 v99, v103, v138, v139
	s_nop 0
	s_waitcnt lgkmcnt(6)
	v_mfma_f32_32x32x16_bf16 v[18:33], v[4:7], v[82:85], v[18:33]
	v_max3_f32 v12, v98, v140, v141
	v_max3_f32 v13, v99, v122, v123
	s_nop 0
	s_waitcnt lgkmcnt(4)
	v_mfma_f32_32x32x16_bf16 v[34:49], v[4:7], v[8:11], v[34:49]
	v_max3_f32 v12, v12, v124, v125
	v_max3_f32 v13, v13, v142, v143
	s_nop 0
	s_waitcnt lgkmcnt(2)
	v_mfma_f32_32x32x16_bf16 v[50:65], v[4:7], v[90:93], v[50:65]
	v_max3_f32 v8, v12, v144, v145
	v_max3_f32 v9, v13, v126, v127
	s_nop 0
	s_waitcnt lgkmcnt(0)
	v_mfma_f32_32x32x16_bf16 v[66:81], v[4:7], v[94:97], v[66:81]
	v_max3_f32 v8, v8, v128, v129
	s_nop 0
	v_max_f32_e32 v8, v8, v9
	s_nop 0
	s_add_i32 s4, s86, 0x2000
	s_cmpk_lg_i32 s86, 0x4000
	s_cselect_b32 s89, s4, 0
	s_add_i32 s4, s89, s80
	s_waitcnt vmcnt(0) lgkmcnt(0)
	s_barrier
	s_add_u32 s58, s48, 0xc0000
	s_mov_b32 s5, m0
	s_mov_b32 m0, s4
	s_nop 0
	global_load_lds_dwordx4 v252, s[50:51]
	s_mov_b32 m0, s5
	s_addc_u32 s59, s49, 0
	v_mov_b32_e32 v4, v8
	s_mov_b32 s4, m0
	s_mov_b32 m0, s78
	s_nop 0
	global_load_lds_dwordx4 v250, s[58:59]
	s_mov_b32 m0, s4
	s_add_u32 s58, s48, 0xc0080
	s_nop 0
	v_permlane32_swap_b32_e32 v8, v4
	s_addc_u32 s59, s49, 0
	s_mov_b32 s4, m0
	s_mov_b32 m0, s79
	s_nop 0
	global_load_lds_dwordx4 v250, s[58:59]
	s_mov_b32 m0, s4
	v_add_u32_e32 v178, s86, v249
	v_max_f32_e32 v94, v8, v4
	ds_read_b128 v[90:93], v178
	ds_read_b128 v[82:85], v178 offset:512
	ds_read_b128 v[12:15], v178 offset:2048
	ds_read_b128 v[4:7], v178 offset:2560
	ds_read_b128 v[86:89], v248
	ds_read_b128 v[8:11], v248 offset:1024
	v_add_f32_e32 v17, v251, v17
	v_cmp_lt_f32_e32 vcc, s67, v94
	s_cbranch_vccz .LBB0_435
	v_max_f32_e32 v94, v94, v94
	v_max_f32_e32 v94, 0, v94
	v_exp_f32_e64 v95, -v94
	s_and_saveexec_b64 s[58:59], s[6:7]
	s_cbranch_execz .LBB0_434
	ds_write_b32 v16, v95
	s_branch .LBB0_434
